# attention: causal mask with three rotating condition registers (no pad nops); partial row sums seeded by the first two units (no zeroing)
# baseline (speedup 1.0000x reference)
.Lat_u1x_bar:
	s_barrier
	s_lshr_b32 s4, s69, 1
	s_sub_u32 s4, s52, s4
	s_cmp_gt_i32 s4, s87
	s_cbranch_scc1 .Lat_u1x_noqk
	s_mul_i32 s53, s48, 0x3000
	v_add_u32_e32 v158, s53, v146
	ds_read_b128 v[196:199], v158
	ds_read_b128 v[200:203], v158 offset:512
	ds_read_b128 v[204:207], v158 offset:2048
	ds_read_b128 v[208:211], v158 offset:2560
	ds_read_b128 v[212:215], v158 offset:4096
	ds_read_b128 v[230:233], v158 offset:4608
	ds_read_b128 v[234:237], v158 offset:6144
	ds_read_b128 v[164:167], v158 offset:6656
	ds_read_b128 v[168:171], v158 offset:8192
	ds_read_b128 v[172:175], v158 offset:8704
	ds_read_b128 v[148:151], v158 offset:10240
	ds_read_b128 v[152:155], v158 offset:10752
	s_lshl_b32 s4, s50, 13
	s_add_i32 s4, s4, 0x6000
	s_and_b32 s4, s4, 0x6000
	v_add_u32_e32 v159, s4, v144
	s_waitcnt lgkmcnt(11)
	v_mfma_f32_32x32x16_bf16 v[238:253], v[196:199], v[100:103], v[104:119]
	ds_read_b64_tr_b16 v[196:197], v159 offset:36864
	ds_read_b64_tr_b16 v[198:199], v159 offset:37376
	v_exp_f32_e32 v64, v64
	v_exp_f32_e32 v65, v65
	v_exp_f32_e32 v66, v66
	v_exp_f32_e32 v67, v67
	s_waitcnt lgkmcnt(12)
	v_mfma_f32_32x32x16_bf16 v[180:195], v[200:203], v[100:103], v[104:119]
	ds_read_b64_tr_b16 v[200:201], v159 offset:37888
	ds_read_b64_tr_b16 v[202:203], v159 offset:38400
	v_add_f32_e32 v156, v64, v65
	v_cvt_pk_bf16_f32 v64, v64, v65
	v_add_f32_e32 v157, v66, v67
	v_cvt_pk_bf16_f32 v65, v66, v67
	v_exp_f32_e32 v68, v68
	v_exp_f32_e32 v69, v69
	s_waitcnt lgkmcnt(13)
	v_mfma_f32_32x32x16_bf16 v[238:253], v[204:207], v[96:99], v[238:253]
	ds_read_b64_tr_b16 v[204:205], v159 offset:38912
	ds_read_b64_tr_b16 v[206:207], v159 offset:39424
	v_add_f32_e32 v156, v156, v68
	v_add_f32_e32 v156, v156, v69
	v_cvt_pk_bf16_f32 v66, v68, v69
	v_exp_f32_e32 v70, v70
	v_exp_f32_e32 v71, v71
	s_waitcnt lgkmcnt(14)
	v_mfma_f32_32x32x16_bf16 v[180:195], v[208:211], v[96:99], v[180:195]
	ds_read_b64_tr_b16 v[208:209], v159 offset:39936
	ds_read_b64_tr_b16 v[210:211], v159 offset:40448
	v_add_f32_e32 v157, v157, v70
	v_add_f32_e32 v157, v157, v71
	v_cvt_pk_bf16_f32 v67, v70, v71
	v_exp_f32_e32 v72, v72
	v_exp_f32_e32 v73, v73
	s_waitcnt lgkmcnt(15)
	v_mfma_f32_32x32x16_bf16 v[238:253], v[212:215], v[92:95], v[238:253]
	ds_read_b64_tr_b16 v[212:213], v159 offset:40960
	ds_read_b64_tr_b16 v[214:215], v159 offset:41472
	v_add_f32_e32 v156, v156, v72
	v_add_f32_e32 v156, v156, v73
	v_cvt_pk_bf16_f32 v68, v72, v73
	v_exp_f32_e32 v74, v74
	v_exp_f32_e32 v75, v75
	s_waitcnt lgkmcnt(15)
	v_mfma_f32_32x32x16_bf16 v[180:195], v[230:233], v[92:95], v[180:195]
	ds_read_b64_tr_b16 v[230:231], v159 offset:41984
	ds_read_b64_tr_b16 v[232:233], v159 offset:42496
	v_add_f32_e32 v157, v157, v74
	v_add_f32_e32 v157, v157, v75
	v_cvt_pk_bf16_f32 v69, v74, v75
	v_exp_f32_e32 v76, v76
	v_exp_f32_e32 v77, v77
	s_waitcnt lgkmcnt(15)
	v_mfma_f32_32x32x16_bf16 v[238:253], v[234:237], v[88:91], v[238:253]
	ds_read_b64_tr_b16 v[234:235], v159 offset:43008
	ds_read_b64_tr_b16 v[236:237], v159 offset:43520
	v_add_f32_e32 v156, v156, v76
	v_add_f32_e32 v156, v156, v77
	v_cvt_pk_bf16_f32 v70, v76, v77
	v_exp_f32_e32 v78, v78
	v_exp_f32_e32 v79, v79
	s_waitcnt lgkmcnt(15)
	v_mfma_f32_32x32x16_bf16 v[180:195], v[164:167], v[88:91], v[180:195]
	ds_read_b64_tr_b16 v[164:165], v159 offset:44032
	ds_read_b64_tr_b16 v[166:167], v159 offset:44544
	v_add_f32_e32 v157, v157, v78
	v_add_f32_e32 v157, v157, v79
	v_cvt_pk_bf16_f32 v71, v78, v79
	v_exp_f32_e32 v48, v48
	v_exp_f32_e32 v49, v49
	s_waitcnt lgkmcnt(15)
	v_mfma_f32_32x32x16_bf16 v[238:253], v[168:171], v[84:87], v[238:253]
	v_add_f32_e32 v156, v156, v48
	v_add_f32_e32 v156, v156, v49
	v_cvt_pk_bf16_f32 v48, v48, v49
	v_exp_f32_e32 v50, v50
	v_exp_f32_e32 v51, v51
	s_waitcnt lgkmcnt(15)
	v_mfma_f32_32x32x16_bf16 v[180:195], v[172:175], v[84:87], v[180:195]
	v_add_f32_e32 v157, v157, v50
	v_add_f32_e32 v157, v157, v51
	v_cvt_pk_bf16_f32 v49, v50, v51
	v_exp_f32_e32 v52, v52
	v_exp_f32_e32 v53, v53
	s_waitcnt lgkmcnt(15)
	v_mfma_f32_32x32x16_bf16 v[238:253], v[148:151], v[80:83], v[238:253]
	v_add_f32_e32 v156, v156, v52
	v_add_f32_e32 v156, v156, v53
	v_cvt_pk_bf16_f32 v50, v52, v53
	v_exp_f32_e32 v54, v54
	v_exp_f32_e32 v55, v55
	s_waitcnt lgkmcnt(15)
	v_mfma_f32_32x32x16_bf16 v[180:195], v[152:155], v[80:83], v[180:195]
	v_add_f32_e32 v157, v157, v54
	v_add_f32_e32 v157, v157, v55
	v_cvt_pk_bf16_f32 v51, v54, v55
	v_exp_f32_e32 v56, v56
	v_exp_f32_e32 v57, v57
	s_waitcnt lgkmcnt(0)
	v_mfma_f32_32x32x16_bf16 v[16:31], v[196:199], v[64:67], v[16:31]
	v_add_f32_e32 v156, v156, v56
	v_add_f32_e32 v156, v156, v57
	v_cvt_pk_bf16_f32 v52, v56, v57
	v_exp_f32_e32 v58, v58
	v_exp_f32_e32 v59, v59
	v_mfma_f32_32x32x16_bf16 v[32:47], v[212:215], v[64:67], v[32:47]
	s_mul_i32 s53, s48, 0x3000
	s_add_i32 s4, s52, 2
	s_cmp_ge_u32 s4, s86
	s_cbranch_scc1 .Lat_u1x_nodma
	s_add_i32 s4, s53, 0xffffd000
	s_cmp_lg_u32 s48, 0
	s_cselect_b32 s4, s4, 0x6000
	s_add_i32 s5, s4, s97
	s_mov_b32 m0, s5
	s_add_i32 s4, s4, s72
	global_load_lds_dwordx4 v[126:127], off
	s_mov_b32 m0, s4
	s_cmp_lt_u32 s69, 4
	s_cbranch_scc0 .Lat_u1x_nok2
	global_load_lds_dwordx4 v[14:15], off

; __device__ __forceinline__ void cmask(f32x16& p0, f32x16& p1, int jb, int qrel, int hi) {
;     const float NEG = -INFINITY; const int kb = 64 * jb + 4 * hi;
; #pragma unroll
;     for (int r = 0; r < 16; ++r) { const int kv = kb + (r & 3) + 8 * (r >> 2); if (kv > qrel) p0[r] = NEG; if (kv + 32 > qrel) p1[r] = NEG; }
; }
.Lat_u1x_nodma:
	v_lshl_add_u64 v[126:127], v[126:127], 0, s[34:35]
	v_lshl_add_u64 v[14:15], v[14:15], 0, s[20:21]
	v_lshl_add_u64 v[124:125], v[124:125], 0, s[34:35]
	v_add_f32_e32 v157, v157, v58
	v_add_f32_e32 v157, v157, v59
	v_cvt_pk_bf16_f32 v53, v58, v59
	v_exp_f32_e32 v60, v60
	v_exp_f32_e32 v61, v61
	v_mfma_f32_32x32x16_bf16 v[16:31], v[200:203], v[68:71], v[16:31]
	v_add_f32_e32 v156, v156, v60
	v_add_f32_e32 v156, v156, v61
	v_cvt_pk_bf16_f32 v54, v60, v61
	v_exp_f32_e32 v62, v62
	v_exp_f32_e32 v63, v63
	v_mfma_f32_32x32x16_bf16 v[32:47], v[230:233], v[68:71], v[32:47]
	v_add_f32_e32 v157, v157, v62
	v_add_f32_e32 v157, v157, v63
	v_cvt_pk_bf16_f32 v55, v62, v63
	s_nop 1
	v_mfma_f32_32x32x16_bf16 v[16:31], v[204:207], v[48:51], v[16:31]
	v_mfma_f32_32x32x16_bf16 v[32:47], v[234:237], v[48:51], v[32:47]
	v_mfma_f32_32x32x16_bf16 v[16:31], v[208:211], v[52:55], v[16:31]
	v_mfma_f32_32x32x16_bf16 v[32:47], v[164:167], v[52:55], v[32:47]
	v_add_f32_e32 v156, v156, v157
	v_add_f32_e32 v128, v128, v156
	s_cmp_lt_u32 s52, s87
	s_cbranch_scc1 .Lat_u1x_nomask
	s_sub_i32 s4, s52, s87
	s_lshl_b32 s4, s4, 6
	s_nop 7
	s_nop 7
	v_lshl_add_u32 v147, v141, 2, s4
	v_sub_u32_e32 v147, v145, v147
	s_nop 0
	v_cmp_gt_i32_e32 vcc, 0, v147
	v_cmp_gt_i32_e64 s[4:5], 1, v147
	v_cmp_gt_i32_e64 s[46:47], 2, v147
	v_cndmask_b32_e32 v238, v238, v220, vcc
	v_cmp_gt_i32_e32 vcc, 3, v147
	v_cndmask_b32_e64 v239, v239, v220, s[4:5]
	v_cmp_gt_i32_e64 s[4:5], 8, v147
	v_cndmask_b32_e64 v240, v240, v220, s[46:47]
	v_cmp_gt_i32_e64 s[46:47], 9, v147
	v_cndmask_b32_e32 v241, v241, v220, vcc
	v_cmp_gt_i32_e32 vcc, 10, v147
	v_cndmask_b32_e64 v242, v242, v220, s[4:5]
	v_cmp_gt_i32_e64 s[4:5], 11, v147
	v_cndmask_b32_e64 v243, v243, v220, s[46:47]
	v_cmp_gt_i32_e64 s[46:47], 16, v147
	v_cndmask_b32_e32 v244, v244, v220, vcc
	v_cmp_gt_i32_e32 vcc, 17, v147
	v_cndmask_b32_e64 v245, v245, v220, s[4:5]
	v_cmp_gt_i32_e64 s[4:5], 18, v147
	v_cndmask_b32_e64 v246, v246, v220, s[46:47]
	v_cmp_gt_i32_e64 s[46:47], 19, v147
	v_cndmask_b32_e32 v247, v247, v220, vcc
	v_cmp_gt_i32_e32 vcc, 24, v147
	v_cndmask_b32_e64 v248, v248, v220, s[4:5]
	v_cmp_gt_i32_e64 s[4:5], 25, v147
	v_cndmask_b32_e64 v249, v249, v220, s[46:47]
	v_cmp_gt_i32_e64 s[46:47], 26, v147
	v_cndmask_b32_e32 v250, v250, v220, vcc
	v_cmp_gt_i32_e32 vcc, 27, v147
	v_cndmask_b32_e64 v251, v251, v220, s[4:5]
	v_cmp_gt_i32_e64 s[4:5], 32, v147
	v_cndmask_b32_e64 v252, v252, v220, s[46:47]
	v_cmp_gt_i32_e64 s[46:47], 33, v147
	v_cndmask_b32_e32 v253, v253, v220, vcc
	v_cmp_gt_i32_e32 vcc, 34, v147
	v_cndmask_b32_e64 v180, v180, v220, s[4:5]
	v_cmp_gt_i32_e64 s[4:5], 35, v147
	v_cndmask_b32_e64 v181, v181, v220, s[46:47]
	v_cmp_gt_i32_e64 s[46:47], 40, v147
	v_cndmask_b32_e32 v182, v182, v220, vcc
	v_cmp_gt_i32_e32 vcc, 41, v147
	v_cndmask_b32_e64 v183, v183, v220, s[4:5]
	v_cmp_gt_i32_e64 s[4:5], 42, v147
	v_cndmask_b32_e64 v184, v184, v220, s[46:47]
	v_cmp_gt_i32_e64 s[46:47], 43, v147
	v_cndmask_b32_e32 v185, v185, v220, vcc
	v_cmp_gt_i32_e32 vcc, 48, v147
	v_cndmask_b32_e64 v186, v186, v220, s[4:5]
	v_cmp_gt_i32_e64 s[4:5], 49, v147
	v_cndmask_b32_e64 v187, v187, v220, s[46:47]
	v_cmp_gt_i32_e64 s[46:47], 50, v147
	v_cndmask_b32_e32 v188, v188, v220, vcc
	v_cmp_gt_i32_e32 vcc, 51, v147
	v_cndmask_b32_e64 v189, v189, v220, s[4:5]
	v_cmp_gt_i32_e64 s[4:5], 56, v147
	v_cndmask_b32_e64 v190, v190, v220, s[46:47]
	v_cmp_gt_i32_e64 s[46:47], 57, v147
	v_cndmask_b32_e32 v191, v191, v220, vcc
	v_cmp_gt_i32_e32 vcc, 58, v147
	v_cndmask_b32_e64 v192, v192, v220, s[4:5]
	v_cmp_gt_i32_e64 s[4:5], 59, v147
	v_cndmask_b32_e64 v193, v193, v220, s[46:47]
	v_cndmask_b32_e32 v194, v194, v220, vcc
	v_cndmask_b32_e64 v195, v195, v220, s[4:5]

.Lat_u1y_bar:
	s_barrier
	s_lshr_b32 s4, s69, 1
	s_sub_u32 s4, s52, s4
	s_cmp_gt_i32 s4, s87
	s_cbranch_scc1 .Lat_u1y_noqk
	s_mul_i32 s53, s48, 0x3000
	v_add_u32_e32 v158, s53, v146
	ds_read_b128 v[196:199], v158
	ds_read_b128 v[200:203], v158 offset:512
	ds_read_b128 v[204:207], v158 offset:2048
	ds_read_b128 v[208:211], v158 offset:2560
	ds_read_b128 v[212:215], v158 offset:4096
	ds_read_b128 v[230:233], v158 offset:4608
	ds_read_b128 v[234:237], v158 offset:6144
	ds_read_b128 v[164:167], v158 offset:6656
	ds_read_b128 v[168:171], v158 offset:8192
	ds_read_b128 v[172:175], v158 offset:8704
	ds_read_b128 v[148:151], v158 offset:10240
	ds_read_b128 v[152:155], v158 offset:10752
	s_lshl_b32 s4, s50, 13
	s_add_i32 s4, s4, 0x6000
	s_and_b32 s4, s4, 0x6000
	v_add_u32_e32 v159, s4, v144
	s_waitcnt lgkmcnt(11)
	v_mfma_f32_32x32x16_bf16 v[64:79], v[196:199], v[100:103], v[104:119]
	ds_read_b64_tr_b16 v[196:197], v159 offset:36864
	ds_read_b64_tr_b16 v[198:199], v159 offset:37376
	v_exp_f32_e32 v238, v238
	v_exp_f32_e32 v239, v239
	v_exp_f32_e32 v240, v240
	v_exp_f32_e32 v241, v241
	s_waitcnt lgkmcnt(12)
	v_mfma_f32_32x32x16_bf16 v[48:63], v[200:203], v[100:103], v[104:119]
	ds_read_b64_tr_b16 v[200:201], v159 offset:37888
	ds_read_b64_tr_b16 v[202:203], v159 offset:38400
	v_add_f32_e32 v156, v238, v239
	v_cvt_pk_bf16_f32 v238, v238, v239
	v_add_f32_e32 v157, v240, v241
	v_cvt_pk_bf16_f32 v239, v240, v241
	v_exp_f32_e32 v242, v242
	v_exp_f32_e32 v243, v243
	s_waitcnt lgkmcnt(13)
	v_mfma_f32_32x32x16_bf16 v[64:79], v[204:207], v[96:99], v[64:79]
	ds_read_b64_tr_b16 v[204:205], v159 offset:38912
	ds_read_b64_tr_b16 v[206:207], v159 offset:39424
	v_add_f32_e32 v156, v156, v242
	v_add_f32_e32 v156, v156, v243
	v_cvt_pk_bf16_f32 v240, v242, v243
	v_exp_f32_e32 v244, v244
	v_exp_f32_e32 v245, v245
	s_waitcnt lgkmcnt(14)
	v_mfma_f32_32x32x16_bf16 v[48:63], v[208:211], v[96:99], v[48:63]
	ds_read_b64_tr_b16 v[208:209], v159 offset:39936
	ds_read_b64_tr_b16 v[210:211], v159 offset:40448
	v_add_f32_e32 v157, v157, v244
	v_add_f32_e32 v157, v157, v245
	v_cvt_pk_bf16_f32 v241, v244, v245
	v_exp_f32_e32 v246, v246
	v_exp_f32_e32 v247, v247
	s_waitcnt lgkmcnt(15)
	v_mfma_f32_32x32x16_bf16 v[64:79], v[212:215], v[92:95], v[64:79]
	ds_read_b64_tr_b16 v[212:213], v159 offset:40960
	ds_read_b64_tr_b16 v[214:215], v159 offset:41472
	v_add_f32_e32 v156, v156, v246
	v_add_f32_e32 v156, v156, v247
	v_cvt_pk_bf16_f32 v242, v246, v247
	v_exp_f32_e32 v248, v248
	v_exp_f32_e32 v249, v249
	s_waitcnt lgkmcnt(15)
	v_mfma_f32_32x32x16_bf16 v[48:63], v[230:233], v[92:95], v[48:63]
	ds_read_b64_tr_b16 v[230:231], v159 offset:41984
	ds_read_b64_tr_b16 v[232:233], v159 offset:42496
	v_add_f32_e32 v157, v157, v248
	v_add_f32_e32 v157, v157, v249
	v_cvt_pk_bf16_f32 v243, v248, v249
	v_exp_f32_e32 v250, v250
	v_exp_f32_e32 v251, v251
	s_waitcnt lgkmcnt(15)
	v_mfma_f32_32x32x16_bf16 v[64:79], v[234:237], v[88:91], v[64:79]
	ds_read_b64_tr_b16 v[234:235], v159 offset:43008
	ds_read_b64_tr_b16 v[236:237], v159 offset:43520
	v_add_f32_e32 v156, v156, v250
	v_add_f32_e32 v156, v156, v251
	v_cvt_pk_bf16_f32 v244, v250, v251
	v_exp_f32_e32 v252, v252
	v_exp_f32_e32 v253, v253
	s_waitcnt lgkmcnt(15)
	v_mfma_f32_32x32x16_bf16 v[48:63], v[164:167], v[88:91], v[48:63]
	ds_read_b64_tr_b16 v[164:165], v159 offset:44032
	ds_read_b64_tr_b16 v[166:167], v159 offset:44544
	v_add_f32_e32 v157, v157, v252
	v_add_f32_e32 v157, v157, v253
	v_cvt_pk_bf16_f32 v245, v252, v253
	v_exp_f32_e32 v180, v180
	v_exp_f32_e32 v181, v181
	s_waitcnt lgkmcnt(15)
	v_mfma_f32_32x32x16_bf16 v[64:79], v[168:171], v[84:87], v[64:79]
	v_add_f32_e32 v156, v156, v180
	v_add_f32_e32 v156, v156, v181
	v_cvt_pk_bf16_f32 v180, v180, v181
	v_exp_f32_e32 v182, v182
	v_exp_f32_e32 v183, v183
	s_waitcnt lgkmcnt(15)
	v_mfma_f32_32x32x16_bf16 v[48:63], v[172:175], v[84:87], v[48:63]
	v_add_f32_e32 v157, v157, v182
	v_add_f32_e32 v157, v157, v183
	v_cvt_pk_bf16_f32 v181, v182, v183
	v_exp_f32_e32 v184, v184
	v_exp_f32_e32 v185, v185
	s_waitcnt lgkmcnt(15)
	v_mfma_f32_32x32x16_bf16 v[64:79], v[148:151], v[80:83], v[64:79]
	v_add_f32_e32 v156, v156, v184
	v_add_f32_e32 v156, v156, v185
	v_cvt_pk_bf16_f32 v182, v184, v185
	v_exp_f32_e32 v186, v186
	v_exp_f32_e32 v187, v187
	s_waitcnt lgkmcnt(15)
	v_mfma_f32_32x32x16_bf16 v[48:63], v[152:155], v[80:83], v[48:63]
	v_add_f32_e32 v157, v157, v186
	v_add_f32_e32 v157, v157, v187
	v_cvt_pk_bf16_f32 v183, v186, v187
	v_exp_f32_e32 v188, v188
	v_exp_f32_e32 v189, v189
	s_waitcnt lgkmcnt(0)
	v_mfma_f32_32x32x16_bf16 v[16:31], v[196:199], v[238:241], v[16:31]
	v_add_f32_e32 v156, v156, v188
	v_add_f32_e32 v156, v156, v189
	v_cvt_pk_bf16_f32 v184, v188, v189
	v_exp_f32_e32 v190, v190
	v_exp_f32_e32 v191, v191
	v_mfma_f32_32x32x16_bf16 v[32:47], v[212:215], v[238:241], v[32:47]
	s_mul_i32 s53, s48, 0x3000
	s_add_i32 s4, s52, 2
	s_cmp_ge_u32 s4, s86
	s_cbranch_scc1 .Lat_u1y_nodma
	s_add_i32 s4, s53, 0xffffd000
	s_cmp_lg_u32 s48, 0
	s_cselect_b32 s4, s4, 0x6000
	s_add_i32 s5, s4, s97
	s_mov_b32 m0, s5
	s_add_i32 s4, s4, s72
	global_load_lds_dwordx4 v[126:127], off
	s_mov_b32 m0, s4
	s_cmp_lt_u32 s69, 4
	s_cbranch_scc0 .Lat_u1y_nok2
	global_load_lds_dwordx4 v[14:15], off

; __device__ __forceinline__ void cmask(f32x16& p0, f32x16& p1, int jb, int qrel, int hi) {
;     const float NEG = -INFINITY; const int kb = 64 * jb + 4 * hi;
; #pragma unroll
;     for (int r = 0; r < 16; ++r) { const int kv = kb + (r & 3) + 8 * (r >> 2); if (kv > qrel) p0[r] = NEG; if (kv + 32 > qrel) p1[r] = NEG; }
; }
.Lat_u1y_nodma:
	v_lshl_add_u64 v[126:127], v[126:127], 0, s[34:35]
	v_lshl_add_u64 v[14:15], v[14:15], 0, s[20:21]
	v_lshl_add_u64 v[124:125], v[124:125], 0, s[34:35]
	v_add_f32_e32 v157, v157, v190
	v_add_f32_e32 v157, v157, v191
	v_cvt_pk_bf16_f32 v185, v190, v191
	v_exp_f32_e32 v192, v192
	v_exp_f32_e32 v193, v193
	v_mfma_f32_32x32x16_bf16 v[16:31], v[200:203], v[242:245], v[16:31]
	v_add_f32_e32 v156, v156, v192
	v_add_f32_e32 v156, v156, v193
	v_cvt_pk_bf16_f32 v186, v192, v193
	v_exp_f32_e32 v194, v194
	v_exp_f32_e32 v195, v195
	v_mfma_f32_32x32x16_bf16 v[32:47], v[230:233], v[242:245], v[32:47]
	v_add_f32_e32 v157, v157, v194
	v_add_f32_e32 v157, v157, v195
	v_cvt_pk_bf16_f32 v187, v194, v195
	s_nop 1
	v_mfma_f32_32x32x16_bf16 v[16:31], v[204:207], v[180:183], v[16:31]
	v_mfma_f32_32x32x16_bf16 v[32:47], v[234:237], v[180:183], v[32:47]
	v_mfma_f32_32x32x16_bf16 v[16:31], v[208:211], v[184:187], v[16:31]
	v_mfma_f32_32x32x16_bf16 v[32:47], v[164:167], v[184:187], v[32:47]
	v_add_f32_e32 v156, v156, v157
	v_add_f32_e32 v128, v128, v156
	s_cmp_lt_u32 s52, s87
	s_cbranch_scc1 .Lat_u1y_nomask
	s_sub_i32 s4, s52, s87
	s_lshl_b32 s4, s4, 6
	s_nop 7
	s_nop 7
	v_lshl_add_u32 v147, v141, 2, s4
	v_sub_u32_e32 v147, v145, v147
	s_nop 0
	v_cmp_gt_i32_e32 vcc, 0, v147
	v_cmp_gt_i32_e64 s[4:5], 1, v147
	v_cmp_gt_i32_e64 s[46:47], 2, v147
	v_cndmask_b32_e32 v64, v64, v220, vcc
	v_cmp_gt_i32_e32 vcc, 3, v147
	v_cndmask_b32_e64 v65, v65, v220, s[4:5]
	v_cmp_gt_i32_e64 s[4:5], 8, v147
	v_cndmask_b32_e64 v66, v66, v220, s[46:47]
	v_cmp_gt_i32_e64 s[46:47], 9, v147
	v_cndmask_b32_e32 v67, v67, v220, vcc
	v_cmp_gt_i32_e32 vcc, 10, v147
	v_cndmask_b32_e64 v68, v68, v220, s[4:5]
	v_cmp_gt_i32_e64 s[4:5], 11, v147
	v_cndmask_b32_e64 v69, v69, v220, s[46:47]
	v_cmp_gt_i32_e64 s[46:47], 16, v147
	v_cndmask_b32_e32 v70, v70, v220, vcc
	v_cmp_gt_i32_e32 vcc, 17, v147
	v_cndmask_b32_e64 v71, v71, v220, s[4:5]
	v_cmp_gt_i32_e64 s[4:5], 18, v147
	v_cndmask_b32_e64 v72, v72, v220, s[46:47]
	v_cmp_gt_i32_e64 s[46:47], 19, v147
	v_cndmask_b32_e32 v73, v73, v220, vcc
	v_cmp_gt_i32_e32 vcc, 24, v147
	v_cndmask_b32_e64 v74, v74, v220, s[4:5]
	v_cmp_gt_i32_e64 s[4:5], 25, v147
	v_cndmask_b32_e64 v75, v75, v220, s[46:47]
	v_cmp_gt_i32_e64 s[46:47], 26, v147
	v_cndmask_b32_e32 v76, v76, v220, vcc
	v_cmp_gt_i32_e32 vcc, 27, v147
	v_cndmask_b32_e64 v77, v77, v220, s[4:5]
	v_cmp_gt_i32_e64 s[4:5], 32, v147
	v_cndmask_b32_e64 v78, v78, v220, s[46:47]
	v_cmp_gt_i32_e64 s[46:47], 33, v147
	v_cndmask_b32_e32 v79, v79, v220, vcc
	v_cmp_gt_i32_e32 vcc, 34, v147
	v_cndmask_b32_e64 v48, v48, v220, s[4:5]
	v_cmp_gt_i32_e64 s[4:5], 35, v147
	v_cndmask_b32_e64 v49, v49, v220, s[46:47]
	v_cmp_gt_i32_e64 s[46:47], 40, v147
	v_cndmask_b32_e32 v50, v50, v220, vcc
	v_cmp_gt_i32_e32 vcc, 41, v147
	v_cndmask_b32_e64 v51, v51, v220, s[4:5]
	v_cmp_gt_i32_e64 s[4:5], 42, v147
	v_cndmask_b32_e64 v52, v52, v220, s[46:47]
	v_cmp_gt_i32_e64 s[46:47], 43, v147
	v_cndmask_b32_e32 v53, v53, v220, vcc
	v_cmp_gt_i32_e32 vcc, 48, v147
	v_cndmask_b32_e64 v54, v54, v220, s[4:5]
	v_cmp_gt_i32_e64 s[4:5], 49, v147
	v_cndmask_b32_e64 v55, v55, v220, s[46:47]
	v_cmp_gt_i32_e64 s[46:47], 50, v147
	v_cndmask_b32_e32 v56, v56, v220, vcc
	v_cmp_gt_i32_e32 vcc, 51, v147
	v_cndmask_b32_e64 v57, v57, v220, s[4:5]
	v_cmp_gt_i32_e64 s[4:5], 56, v147
	v_cndmask_b32_e64 v58, v58, v220, s[46:47]
	v_cmp_gt_i32_e64 s[46:47], 57, v147
	v_cndmask_b32_e32 v59, v59, v220, vcc
	v_cmp_gt_i32_e32 vcc, 58, v147
	v_cndmask_b32_e64 v60, v60, v220, s[4:5]
	v_cmp_gt_i32_e64 s[4:5], 59, v147
	v_cndmask_b32_e64 v61, v61, v220, s[46:47]
	v_cndmask_b32_e32 v62, v62, v220, vcc
	v_cndmask_b32_e64 v63, v63, v220, s[4:5]

; #define V_LOAD(vs) do { const LAS char* vp_ = vp0 + (vs) * VSLOT; \
;         _Pragma("unroll") for (int i_ = 0; i_ < 8; ++i_) { vlo[i_] = vtr(vp_ + ((i_ >> 2) * 4096 + (i_ & 3) * 1024)); vhi[i_] = vtr(vp_ + ((i_ >> 2) * 4096 + (i_ & 3) * 1024 + 512)); } SBAR(); } while (0)
; __device__ __forceinline__ void attn_unit(int b, int h, int qb, const bf16* Q, const bf16* __restrict__ Kn, const bf16* __restrict__ Kpe, const bf16* __restrict__ V, bf16* O, float* ASS, LAS char* shm) {
;     ...
;         V_LOAD((vs + 3) & 3);
;         SOFTMAX();
;         PV_MMA();
.Lat_u1_tail:
	s_add_u32 s4, s86, 2
	s_lshl_b32 s5, s4, 16
	s_sub_u32 s5, 0, s5
	s_mov_b32 s53, -1
	s_mov_b32 vcc_lo, s5
	s_mov_b32 vcc_hi, s53
	v_lshl_add_u64 v[168:169], v[126:127], 0, vcc
	global_load_dword v155, v[168:169], off
	v_lshl_add_u64 v[168:169], v[168:169], 0, s[34:35]
	global_load_dword v155, v[168:169], off
	v_lshl_add_u64 v[168:169], v[124:125], 0, vcc
	global_load_dword v155, v[168:169], off
	v_lshl_add_u64 v[168:169], v[168:169], 0, s[34:35]
	global_load_dword v155, v[168:169], off
	s_lshl_b32 s5, s4, 12
	s_sub_u32 s5, 0, s5
	s_mov_b32 vcc_lo, s5
	v_lshl_add_u64 v[168:169], v[14:15], 0, vcc
	global_load_dword v155, v[168:169], off
	v_lshl_add_u64 v[168:169], v[168:169], 0, s[20:21]
	global_load_dword v155, v[168:169], off
	s_lshl_b32 s4, s69, 5
	s_add_u32 s4, s4, s88
	s_mul_i32 s4, s4, 0x600
	s_add_u32 s4, s4, s64
	s_add_u32 s4, s4, s78
	s_addc_u32 s5, s79, 0
	v_mul_u32_u24_e32 v172, 0x600, v140
	global_load_dword v155, v172, s[4:5]
	global_load_dword v155, v172, s[4:5] offset:64
	global_load_dword v155, v172, s[4:5] offset:128
	s_waitcnt lgkmcnt(0)
	s_lshr_b32 s4, s69, 1
	s_sub_u32 s4, s52, s4
	s_sub_u32 s4, s4, 1
	s_cmp_gt_i32 s4, s87
	s_cbranch_scc1 .Lat_u1t_skip
	s_lshl_b32 s4, s50, 13
	s_add_i32 s4, s4, 0x6000
	s_and_b32 s4, s4, 0x6000
	v_add_u32_e32 v159, s4, v144
	ds_read_b64_tr_b16 v[196:197], v159 offset:36864
	ds_read_b64_tr_b16 v[198:199], v159 offset:37376
	ds_read_b64_tr_b16 v[200:201], v159 offset:37888
	ds_read_b64_tr_b16 v[202:203], v159 offset:38400
	ds_read_b64_tr_b16 v[204:205], v159 offset:38912
	ds_read_b64_tr_b16 v[206:207], v159 offset:39424
	ds_read_b64_tr_b16 v[208:209], v159 offset:39936
	ds_read_b64_tr_b16 v[210:211], v159 offset:40448
	ds_read_b64_tr_b16 v[212:213], v159 offset:40960
	ds_read_b64_tr_b16 v[214:215], v159 offset:41472
	ds_read_b64_tr_b16 v[230:231], v159 offset:41984
	ds_read_b64_tr_b16 v[232:233], v159 offset:42496
	ds_read_b64_tr_b16 v[234:235], v159 offset:43008
	ds_read_b64_tr_b16 v[236:237], v159 offset:43520
	ds_read_b64_tr_b16 v[164:165], v159 offset:44032
	ds_read_b64_tr_b16 v[166:167], v159 offset:44544
	v_exp_f32_e32 v238, v238
	v_exp_f32_e32 v239, v239
	v_exp_f32_e32 v240, v240
	v_exp_f32_e32 v241, v241
	v_add_f32_e32 v156, v238, v239
	v_cvt_pk_bf16_f32 v238, v238, v239
	v_add_f32_e32 v157, v240, v241
	v_cvt_pk_bf16_f32 v239, v240, v241
	v_exp_f32_e32 v242, v242
	v_exp_f32_e32 v243, v243
	v_add_f32_e32 v156, v156, v242
	v_add_f32_e32 v156, v156, v243
	v_cvt_pk_bf16_f32 v240, v242, v243
	v_exp_f32_e32 v244, v244
	v_exp_f32_e32 v245, v245
	v_add_f32_e32 v157, v157, v244
	v_add_f32_e32 v157, v157, v245
	v_cvt_pk_bf16_f32 v241, v244, v245
	v_exp_f32_e32 v246, v246
	v_exp_f32_e32 v247, v247
	v_add_f32_e32 v156, v156, v246
	v_add_f32_e32 v156, v156, v247
	v_cvt_pk_bf16_f32 v242, v246, v247
	v_exp_f32_e32 v248, v248
	v_exp_f32_e32 v249, v249
	v_add_f32_e32 v157, v157, v248
	v_add_f32_e32 v157, v157, v249
	v_cvt_pk_bf16_f32 v243, v248, v249
	v_exp_f32_e32 v250, v250
	v_exp_f32_e32 v251, v251
	v_add_f32_e32 v156, v156, v250
	v_add_f32_e32 v156, v156, v251
	v_cvt_pk_bf16_f32 v244, v250, v251
	v_exp_f32_e32 v252, v252
	v_exp_f32_e32 v253, v253
	v_add_f32_e32 v157, v157, v252
	v_add_f32_e32 v157, v157, v253
	v_cvt_pk_bf16_f32 v245, v252, v253
	v_exp_f32_e32 v180, v180
	v_exp_f32_e32 v181, v181
	v_add_f32_e32 v156, v156, v180
	v_add_f32_e32 v156, v156, v181
	v_cvt_pk_bf16_f32 v180, v180, v181
	v_exp_f32_e32 v182, v182
	v_exp_f32_e32 v183, v183
	v_add_f32_e32 v157, v157, v182
	v_add_f32_e32 v157, v157, v183
	v_cvt_pk_bf16_f32 v181, v182, v183
	v_exp_f32_e32 v184, v184
	v_exp_f32_e32 v185, v185
	v_add_f32_e32 v156, v156, v184
	v_add_f32_e32 v156, v156, v185
	v_cvt_pk_bf16_f32 v182, v184, v185
	v_exp_f32_e32 v186, v186
	v_exp_f32_e32 v187, v187
	v_add_f32_e32 v157, v157, v186
	v_add_f32_e32 v157, v157, v187
	v_cvt_pk_bf16_f32 v183, v186, v187
	v_exp_f32_e32 v188, v188
	v_exp_f32_e32 v189, v189
	v_add_f32_e32 v156, v156, v188
	v_add_f32_e32 v156, v156, v189
	v_cvt_pk_bf16_f32 v184, v188, v189
	v_exp_f32_e32 v190, v190
	v_exp_f32_e32 v191, v191
	v_add_f32_e32 v157, v157, v190
	v_add_f32_e32 v157, v157, v191
	v_cvt_pk_bf16_f32 v185, v190, v191
	v_exp_f32_e32 v192, v192
	v_exp_f32_e32 v193, v193
	v_add_f32_e32 v156, v156, v192
	v_add_f32_e32 v156, v156, v193
	v_cvt_pk_bf16_f32 v186, v192, v193
	v_exp_f32_e32 v194, v194
	v_exp_f32_e32 v195, v195
	v_add_f32_e32 v157, v157, v194
	v_add_f32_e32 v157, v157, v195
	v_cvt_pk_bf16_f32 v187, v194, v195
	v_add_f32_e32 v156, v156, v157
	v_add_f32_e32 v128, v128, v156
	s_waitcnt lgkmcnt(0)
	v_mfma_f32_32x32x16_bf16 v[16:31], v[196:199], v[238:241], v[16:31]
	v_mfma_f32_32x32x16_bf16 v[32:47], v[212:215], v[238:241], v[32:47]
	v_mfma_f32_32x32x16_bf16 v[16:31], v[200:203], v[242:245], v[16:31]
	v_mfma_f32_32x32x16_bf16 v[32:47], v[230:233], v[242:245], v[32:47]
	v_mfma_f32_32x32x16_bf16 v[16:31], v[204:207], v[180:183], v[16:31]
	v_mfma_f32_32x32x16_bf16 v[32:47], v[234:237], v[180:183], v[32:47]
	v_mfma_f32_32x32x16_bf16 v[16:31], v[208:211], v[184:187], v[16:31]
	v_mfma_f32_32x32x16_bf16 v[32:47], v[164:167], v[184:187], v[32:47]

; #define V_LOAD(vs) do { const LAS char* vp_ = vp0 + (vs) * VSLOT; \
;         _Pragma("unroll") for (int i_ = 0; i_ < 8; ++i_) { vlo[i_] = vtr(vp_ + ((i_ >> 2) * 4096 + (i_ & 3) * 1024)); vhi[i_] = vtr(vp_ + ((i_ >> 2) * 4096 + (i_ & 3) * 1024 + 512)); } SBAR(); } while (0)
; __device__ __forceinline__ void attn_unit(int b, int h, int qb, const bf16* Q, const bf16* __restrict__ Kn, const bf16* __restrict__ Kpe, const bf16* __restrict__ V, bf16* O, float* ASS, LAS char* shm) {
;     ...
;         V_LOAD((vs + 3) & 3);
;         SOFTMAX();
;         PV_MMA();
.Lat_u1x_noqk:
	s_lshr_b32 s4, s69, 1
	s_sub_u32 s4, s52, s4
	s_sub_u32 s4, s4, 1
	s_cmp_gt_i32 s4, s87
	s_cbranch_scc1 .Lat_u1x_idle
	s_lshl_b32 s4, s50, 13
	s_add_i32 s4, s4, 0x6000
	s_and_b32 s4, s4, 0x6000
	v_add_u32_e32 v159, s4, v144
	ds_read_b64_tr_b16 v[196:197], v159 offset:36864
	ds_read_b64_tr_b16 v[198:199], v159 offset:37376
	ds_read_b64_tr_b16 v[200:201], v159 offset:37888
	ds_read_b64_tr_b16 v[202:203], v159 offset:38400
	ds_read_b64_tr_b16 v[204:205], v159 offset:38912
	ds_read_b64_tr_b16 v[206:207], v159 offset:39424
	ds_read_b64_tr_b16 v[208:209], v159 offset:39936
	ds_read_b64_tr_b16 v[210:211], v159 offset:40448
	ds_read_b64_tr_b16 v[212:213], v159 offset:40960
	ds_read_b64_tr_b16 v[214:215], v159 offset:41472
	ds_read_b64_tr_b16 v[230:231], v159 offset:41984
	ds_read_b64_tr_b16 v[232:233], v159 offset:42496
	ds_read_b64_tr_b16 v[234:235], v159 offset:43008
	ds_read_b64_tr_b16 v[236:237], v159 offset:43520
	ds_read_b64_tr_b16 v[164:165], v159 offset:44032
	ds_read_b64_tr_b16 v[166:167], v159 offset:44544
	v_exp_f32_e32 v64, v64
	v_exp_f32_e32 v65, v65
	v_exp_f32_e32 v66, v66
	v_exp_f32_e32 v67, v67
	v_add_f32_e32 v156, v64, v65
	v_cvt_pk_bf16_f32 v64, v64, v65
	v_add_f32_e32 v157, v66, v67
	v_cvt_pk_bf16_f32 v65, v66, v67
	v_exp_f32_e32 v68, v68
	v_exp_f32_e32 v69, v69
	v_add_f32_e32 v156, v156, v68
	v_add_f32_e32 v156, v156, v69
	v_cvt_pk_bf16_f32 v66, v68, v69
	v_exp_f32_e32 v70, v70
	v_exp_f32_e32 v71, v71
	v_add_f32_e32 v157, v157, v70
	v_add_f32_e32 v157, v157, v71
	v_cvt_pk_bf16_f32 v67, v70, v71
	v_exp_f32_e32 v72, v72
	v_exp_f32_e32 v73, v73
	v_add_f32_e32 v156, v156, v72
	v_add_f32_e32 v156, v156, v73
	v_cvt_pk_bf16_f32 v68, v72, v73
	v_exp_f32_e32 v74, v74
	v_exp_f32_e32 v75, v75
	v_add_f32_e32 v157, v157, v74
	v_add_f32_e32 v157, v157, v75
	v_cvt_pk_bf16_f32 v69, v74, v75
	v_exp_f32_e32 v76, v76
	v_exp_f32_e32 v77, v77
	v_add_f32_e32 v156, v156, v76
	v_add_f32_e32 v156, v156, v77
	v_cvt_pk_bf16_f32 v70, v76, v77
	v_exp_f32_e32 v78, v78
	v_exp_f32_e32 v79, v79
	v_add_f32_e32 v157, v157, v78
	v_add_f32_e32 v157, v157, v79
	v_cvt_pk_bf16_f32 v71, v78, v79
	v_exp_f32_e32 v48, v48
	s_nop 1
	s_waitcnt lgkmcnt(0)
	v_mfma_f32_32x32x16_bf16 v[16:31], v[196:199], v[64:67], v[16:31]
	v_exp_f32_e32 v49, v49
	v_add_f32_e32 v156, v156, v48
	v_add_f32_e32 v156, v156, v49
	v_cvt_pk_bf16_f32 v48, v48, v49
	v_exp_f32_e32 v50, v50
	v_exp_f32_e32 v51, v51
	v_add_f32_e32 v157, v157, v50
	v_add_f32_e32 v157, v157, v51
	v_cvt_pk_bf16_f32 v49, v50, v51
	v_exp_f32_e32 v52, v52
	v_mfma_f32_32x32x16_bf16 v[32:47], v[212:215], v[64:67], v[32:47]
	v_exp_f32_e32 v53, v53
	v_add_f32_e32 v156, v156, v52
	v_add_f32_e32 v156, v156, v53
	v_cvt_pk_bf16_f32 v50, v52, v53
	v_exp_f32_e32 v54, v54
	v_exp_f32_e32 v55, v55
	v_add_f32_e32 v157, v157, v54
	v_add_f32_e32 v157, v157, v55
	v_cvt_pk_bf16_f32 v51, v54, v55
	v_exp_f32_e32 v56, v56
	v_mfma_f32_32x32x16_bf16 v[16:31], v[200:203], v[68:71], v[16:31]
	v_exp_f32_e32 v57, v57
	v_add_f32_e32 v156, v156, v56
	v_add_f32_e32 v156, v156, v57
	v_cvt_pk_bf16_f32 v52, v56, v57
	v_exp_f32_e32 v58, v58
	v_exp_f32_e32 v59, v59
	v_add_f32_e32 v157, v157, v58
	v_add_f32_e32 v157, v157, v59
	v_cvt_pk_bf16_f32 v53, v58, v59
	v_exp_f32_e32 v60, v60
	v_mfma_f32_32x32x16_bf16 v[32:47], v[230:233], v[68:71], v[32:47]
	v_exp_f32_e32 v61, v61
	v_add_f32_e32 v156, v156, v60
	v_add_f32_e32 v156, v156, v61
	v_cvt_pk_bf16_f32 v54, v60, v61
	v_exp_f32_e32 v62, v62
	v_exp_f32_e32 v63, v63
	v_add_f32_e32 v157, v157, v62
	v_add_f32_e32 v157, v157, v63
	v_cvt_pk_bf16_f32 v55, v62, v63
	s_nop 1
	v_mfma_f32_32x32x16_bf16 v[16:31], v[204:207], v[48:51], v[16:31]
	v_mfma_f32_32x32x16_bf16 v[32:47], v[234:237], v[48:51], v[32:47]
	v_mfma_f32_32x32x16_bf16 v[16:31], v[208:211], v[52:55], v[16:31]
	v_mfma_f32_32x32x16_bf16 v[32:47], v[164:167], v[52:55], v[32:47]
	v_add_f32_e32 v156, v156, v157
	v_add_f32_e32 v128, v128, v156

; #define V_LOAD(vs) do { const LAS char* vp_ = vp0 + (vs) * VSLOT; \
;         _Pragma("unroll") for (int i_ = 0; i_ < 8; ++i_) { vlo[i_] = vtr(vp_ + ((i_ >> 2) * 4096 + (i_ & 3) * 1024)); vhi[i_] = vtr(vp_ + ((i_ >> 2) * 4096 + (i_ & 3) * 1024 + 512)); } SBAR(); } while (0)
; __device__ __forceinline__ void attn_unit(int b, int h, int qb, const bf16* Q, const bf16* __restrict__ Kn, const bf16* __restrict__ Kpe, const bf16* __restrict__ V, bf16* O, float* ASS, LAS char* shm) {
;     ...
;         V_LOAD((vs + 3) & 3);
;         SOFTMAX();
;         PV_MMA();
.Lat_u1y_noqk:
	s_lshr_b32 s4, s69, 1
	s_sub_u32 s4, s52, s4
	s_sub_u32 s4, s4, 1
	s_cmp_gt_i32 s4, s87
	s_cbranch_scc1 .Lat_u1y_idle
	s_lshl_b32 s4, s50, 13
	s_add_i32 s4, s4, 0x6000
	s_and_b32 s4, s4, 0x6000
	v_add_u32_e32 v159, s4, v144
	ds_read_b64_tr_b16 v[196:197], v159 offset:36864
	ds_read_b64_tr_b16 v[198:199], v159 offset:37376
	ds_read_b64_tr_b16 v[200:201], v159 offset:37888
	ds_read_b64_tr_b16 v[202:203], v159 offset:38400
	ds_read_b64_tr_b16 v[204:205], v159 offset:38912
	ds_read_b64_tr_b16 v[206:207], v159 offset:39424
	ds_read_b64_tr_b16 v[208:209], v159 offset:39936
	ds_read_b64_tr_b16 v[210:211], v159 offset:40448
	ds_read_b64_tr_b16 v[212:213], v159 offset:40960
	ds_read_b64_tr_b16 v[214:215], v159 offset:41472
	ds_read_b64_tr_b16 v[230:231], v159 offset:41984
	ds_read_b64_tr_b16 v[232:233], v159 offset:42496
	ds_read_b64_tr_b16 v[234:235], v159 offset:43008
	ds_read_b64_tr_b16 v[236:237], v159 offset:43520
	ds_read_b64_tr_b16 v[164:165], v159 offset:44032
	ds_read_b64_tr_b16 v[166:167], v159 offset:44544
	v_exp_f32_e32 v238, v238
	v_exp_f32_e32 v239, v239
	v_exp_f32_e32 v240, v240
	v_exp_f32_e32 v241, v241
	v_add_f32_e32 v156, v238, v239
	v_cvt_pk_bf16_f32 v238, v238, v239
	v_add_f32_e32 v157, v240, v241
	v_cvt_pk_bf16_f32 v239, v240, v241
	v_exp_f32_e32 v242, v242
	v_exp_f32_e32 v243, v243
	v_add_f32_e32 v156, v156, v242
	v_add_f32_e32 v156, v156, v243
	v_cvt_pk_bf16_f32 v240, v242, v243
	v_exp_f32_e32 v244, v244
	v_exp_f32_e32 v245, v245
	v_add_f32_e32 v157, v157, v244
	v_add_f32_e32 v157, v157, v245
	v_cvt_pk_bf16_f32 v241, v244, v245
	v_exp_f32_e32 v246, v246
	v_exp_f32_e32 v247, v247
	v_add_f32_e32 v156, v156, v246
	v_add_f32_e32 v156, v156, v247
	v_cvt_pk_bf16_f32 v242, v246, v247
	v_exp_f32_e32 v248, v248
	v_exp_f32_e32 v249, v249
	v_add_f32_e32 v157, v157, v248
	v_add_f32_e32 v157, v157, v249
	v_cvt_pk_bf16_f32 v243, v248, v249
	v_exp_f32_e32 v250, v250
	v_exp_f32_e32 v251, v251
	v_add_f32_e32 v156, v156, v250
	v_add_f32_e32 v156, v156, v251
	v_cvt_pk_bf16_f32 v244, v250, v251
	v_exp_f32_e32 v252, v252
	v_exp_f32_e32 v253, v253
	v_add_f32_e32 v157, v157, v252
	v_add_f32_e32 v157, v157, v253
	v_cvt_pk_bf16_f32 v245, v252, v253
	v_exp_f32_e32 v180, v180
	s_nop 1
	s_waitcnt lgkmcnt(0)
	v_mfma_f32_32x32x16_bf16 v[16:31], v[196:199], v[238:241], v[16:31]
	v_exp_f32_e32 v181, v181
	v_add_f32_e32 v156, v156, v180
	v_add_f32_e32 v156, v156, v181
	v_cvt_pk_bf16_f32 v180, v180, v181
	v_exp_f32_e32 v182, v182
	v_exp_f32_e32 v183, v183
	v_add_f32_e32 v157, v157, v182
	v_add_f32_e32 v157, v157, v183
	v_cvt_pk_bf16_f32 v181, v182, v183
	v_exp_f32_e32 v184, v184
	v_mfma_f32_32x32x16_bf16 v[32:47], v[212:215], v[238:241], v[32:47]
	v_exp_f32_e32 v185, v185
	v_add_f32_e32 v156, v156, v184
	v_add_f32_e32 v156, v156, v185
	v_cvt_pk_bf16_f32 v182, v184, v185
	v_exp_f32_e32 v186, v186
	v_exp_f32_e32 v187, v187
	v_add_f32_e32 v157, v157, v186
	v_add_f32_e32 v157, v157, v187
	v_cvt_pk_bf16_f32 v183, v186, v187
	v_exp_f32_e32 v188, v188
	v_mfma_f32_32x32x16_bf16 v[16:31], v[200:203], v[242:245], v[16:31]
	v_exp_f32_e32 v189, v189
	v_add_f32_e32 v156, v156, v188
	v_add_f32_e32 v156, v156, v189
	v_cvt_pk_bf16_f32 v184, v188, v189
	v_exp_f32_e32 v190, v190
	v_exp_f32_e32 v191, v191
	v_add_f32_e32 v157, v157, v190
	v_add_f32_e32 v157, v157, v191
	v_cvt_pk_bf16_f32 v185, v190, v191
	v_exp_f32_e32 v192, v192
	v_mfma_f32_32x32x16_bf16 v[32:47], v[230:233], v[242:245], v[32:47]
	v_exp_f32_e32 v193, v193
	v_add_f32_e32 v156, v156, v192
	v_add_f32_e32 v156, v156, v193
	v_cvt_pk_bf16_f32 v186, v192, v193
	v_exp_f32_e32 v194, v194
	v_exp_f32_e32 v195, v195
	v_add_f32_e32 v157, v157, v194
	v_add_f32_e32 v157, v157, v195
	v_cvt_pk_bf16_f32 v187, v194, v195
	s_nop 1
	v_mfma_f32_32x32x16_bf16 v[16:31], v[204:207], v[180:183], v[16:31]
	v_mfma_f32_32x32x16_bf16 v[32:47], v[234:237], v[180:183], v[32:47]
	v_mfma_f32_32x32x16_bf16 v[16:31], v[208:211], v[184:187], v[16:31]
	v_mfma_f32_32x32x16_bf16 v[32:47], v[164:167], v[184:187], v[32:47]
	v_add_f32_e32 v156, v156, v157
	v_add_f32_e32 v128, v128, v156

; #define LAS __attribute__((address_space(3)))
; #define DMA_TILE(t, ks, vs) do { glds16(ksrc + (long)(t) * KVBLK * KNP, (unsigned)__builtin_amdgcn_readfirstlane(kdst + (ks) * KSLOT)); \
;         glds16(k2src + (long)(t) * KVBLK * KPP, (unsigned)__builtin_amdgcn_readfirstlane(k2dst + (ks) * KSLOT)); \
;         glds16(vsrc + (long)(t) * KVBLK * VP, (unsigned)__builtin_amdgcn_readfirstlane(vdst + (vs) * VSLOT)); } while (0)
; __device__ __forceinline__ void attn_unit(int b, int h, int qb, const bf16* Q, const bf16* __restrict__ Kn, const bf16* __restrict__ Kpe, const bf16* __restrict__ V, bf16* O, float* ASS, LAS char* shm) {
;     ...
;     const int vb0 = (int)(lds0 + LDS_V) + ((lane >> 4) & 1) * 32 + (lane & 3) * 8 + (4 * hi + ((lane & 15) >> 2)) * 64;
;     const int NT = (q0 + QB) / KVBLK;
;     DMA_TILE(0, 0, 0); DMA_TILE(1, 1, 1);
;     bf16x8 qr[6];
; #pragma unroll
;     for (int d0 = 0; d0 < 6; ++d0) qr[d0] = *reinterpret_cast<const bf16x8*>(&Qw[(long)r32 * QP + d0 * 16 + hi * 8]);
;     asm volatile("" : "+v"(qr[0]), "+v"(qr[1]), "+v"(qr[2]), "+v"(qr[3]), "+v"(qr[4]), "+v"(qr[5]));
;     float m_run = -1e30f, l_run = 0.f; f32x16 o[2]; o[0] = f32x16{}; o[1] = f32x16{};
;     const int qrel = wid * QBLK + r32;
;     f32x16 p0, p1;
;     bf16x8 kf[12]; s16x4 vlo[8], vhi[8]; u32x4 pw0, pw1, pw2, pw3;
;     const LAS char* kp0 = shm + LDS_K + hi * 1024 + r32 * 16;
;     const LAS char* vp0 = shm + LDS_V + ((lane >> 4) & 1) * 32 + (lane & 3) * 8 + (4 * hi + ((lane & 15) >> 2)) * 64;
.Lat_u2x_bar:
	s_barrier
	s_lshr_b32 s4, s56, 1
	s_sub_u32 s4, s62, s4
	s_cmp_gt_i32 s4, s91
	s_cbranch_scc1 .Lat_u2x_noqk
	s_mul_i32 s63, s61, 0x3000
	v_add_u32_e32 v158, s63, v146
	ds_read_b128 v[196:199], v158
	ds_read_b128 v[200:203], v158 offset:512
	ds_read_b128 v[204:207], v158 offset:2048
	ds_read_b128 v[208:211], v158 offset:2560
	ds_read_b128 v[212:215], v158 offset:4096
	ds_read_b128 v[230:233], v158 offset:4608
	ds_read_b128 v[234:237], v158 offset:6144
	ds_read_b128 v[164:167], v158 offset:6656
	ds_read_b128 v[168:171], v158 offset:8192
	ds_read_b128 v[172:175], v158 offset:8704
	ds_read_b128 v[148:151], v158 offset:10240
	ds_read_b128 v[152:155], v158 offset:10752
	s_lshl_b32 s4, s64, 13
	s_add_i32 s4, s4, 0x6000
	s_and_b32 s4, s4, 0x6000
	v_add_u32_e32 v159, s4, v143
	s_waitcnt lgkmcnt(11)
	v_mfma_f32_32x32x16_bf16 v[238:253], v[196:199], v[86:89], v[104:119]
	ds_read_b64_tr_b16 v[196:197], v159 offset:36864
	ds_read_b64_tr_b16 v[198:199], v159 offset:37376
	v_exp_f32_e32 v50, v50
	v_exp_f32_e32 v51, v51
	v_exp_f32_e32 v52, v52
	v_exp_f32_e32 v53, v53
	s_waitcnt lgkmcnt(12)
	v_mfma_f32_32x32x16_bf16 v[180:195], v[200:203], v[86:89], v[104:119]
	ds_read_b64_tr_b16 v[200:201], v159 offset:37888
	ds_read_b64_tr_b16 v[202:203], v159 offset:38400
	v_add_f32_e32 v156, v50, v51
	v_cvt_pk_bf16_f32 v50, v50, v51
	v_add_f32_e32 v157, v52, v53
	v_cvt_pk_bf16_f32 v51, v52, v53
	v_exp_f32_e32 v54, v54
	v_exp_f32_e32 v55, v55
	s_waitcnt lgkmcnt(13)
	v_mfma_f32_32x32x16_bf16 v[238:253], v[204:207], v[82:85], v[238:253]
	ds_read_b64_tr_b16 v[204:205], v159 offset:38912
	ds_read_b64_tr_b16 v[206:207], v159 offset:39424
	v_add_f32_e32 v156, v156, v54
	v_add_f32_e32 v156, v156, v55
	v_cvt_pk_bf16_f32 v52, v54, v55
	v_exp_f32_e32 v56, v56
	v_exp_f32_e32 v57, v57
	s_waitcnt lgkmcnt(14)
	v_mfma_f32_32x32x16_bf16 v[180:195], v[208:211], v[82:85], v[180:195]
	ds_read_b64_tr_b16 v[208:209], v159 offset:39936
	ds_read_b64_tr_b16 v[210:211], v159 offset:40448
	v_add_f32_e32 v157, v157, v56
	v_add_f32_e32 v157, v157, v57
	v_cvt_pk_bf16_f32 v53, v56, v57
	v_exp_f32_e32 v58, v58
	v_exp_f32_e32 v59, v59
	s_waitcnt lgkmcnt(15)
	v_mfma_f32_32x32x16_bf16 v[238:253], v[212:215], v[78:81], v[238:253]
	ds_read_b64_tr_b16 v[212:213], v159 offset:40960
	ds_read_b64_tr_b16 v[214:215], v159 offset:41472
	v_add_f32_e32 v156, v156, v58
	v_add_f32_e32 v156, v156, v59
	v_cvt_pk_bf16_f32 v54, v58, v59
	v_exp_f32_e32 v60, v60
	v_exp_f32_e32 v61, v61
	s_waitcnt lgkmcnt(15)
	v_mfma_f32_32x32x16_bf16 v[180:195], v[230:233], v[78:81], v[180:195]
	ds_read_b64_tr_b16 v[230:231], v159 offset:41984
	ds_read_b64_tr_b16 v[232:233], v159 offset:42496
	v_add_f32_e32 v157, v157, v60
	v_add_f32_e32 v157, v157, v61
	v_cvt_pk_bf16_f32 v55, v60, v61
	v_exp_f32_e32 v62, v62
	v_exp_f32_e32 v63, v63
	s_waitcnt lgkmcnt(15)
	v_mfma_f32_32x32x16_bf16 v[238:253], v[234:237], v[74:77], v[238:253]
	ds_read_b64_tr_b16 v[234:235], v159 offset:43008
	ds_read_b64_tr_b16 v[236:237], v159 offset:43520
	v_add_f32_e32 v156, v156, v62
	v_add_f32_e32 v156, v156, v63
	v_cvt_pk_bf16_f32 v56, v62, v63
	v_exp_f32_e32 v64, v64
	v_exp_f32_e32 v65, v65
	s_waitcnt lgkmcnt(15)
	v_mfma_f32_32x32x16_bf16 v[180:195], v[164:167], v[74:77], v[180:195]
	ds_read_b64_tr_b16 v[164:165], v159 offset:44032
	ds_read_b64_tr_b16 v[166:167], v159 offset:44544
	v_add_f32_e32 v157, v157, v64
	v_add_f32_e32 v157, v157, v65
	v_cvt_pk_bf16_f32 v57, v64, v65
	v_exp_f32_e32 v34, v34
	v_exp_f32_e32 v35, v35
	s_waitcnt lgkmcnt(15)
	v_mfma_f32_32x32x16_bf16 v[238:253], v[168:171], v[70:73], v[238:253]
	v_add_f32_e32 v156, v156, v34
	v_add_f32_e32 v156, v156, v35
	v_cvt_pk_bf16_f32 v34, v34, v35
	v_exp_f32_e32 v36, v36
	v_exp_f32_e32 v37, v37
	s_waitcnt lgkmcnt(15)
	v_mfma_f32_32x32x16_bf16 v[180:195], v[172:175], v[70:73], v[180:195]
	v_add_f32_e32 v157, v157, v36
	v_add_f32_e32 v157, v157, v37
	v_cvt_pk_bf16_f32 v35, v36, v37
	v_exp_f32_e32 v38, v38
	v_exp_f32_e32 v39, v39
	s_waitcnt lgkmcnt(15)
	v_mfma_f32_32x32x16_bf16 v[238:253], v[148:151], v[66:69], v[238:253]
	v_add_f32_e32 v156, v156, v38
	v_add_f32_e32 v156, v156, v39
	v_cvt_pk_bf16_f32 v36, v38, v39
	v_exp_f32_e32 v40, v40
	v_exp_f32_e32 v41, v41
	s_waitcnt lgkmcnt(15)
	v_mfma_f32_32x32x16_bf16 v[180:195], v[152:155], v[66:69], v[180:195]
	v_add_f32_e32 v157, v157, v40
	v_add_f32_e32 v157, v157, v41
	v_cvt_pk_bf16_f32 v37, v40, v41
	v_exp_f32_e32 v42, v42
	v_exp_f32_e32 v43, v43
	s_waitcnt lgkmcnt(0)
	v_mfma_f32_32x32x16_bf16 v[18:33], v[196:199], v[50:53], v[18:33]
	v_add_f32_e32 v156, v156, v42
	v_add_f32_e32 v156, v156, v43
	v_cvt_pk_bf16_f32 v38, v42, v43
	v_exp_f32_e32 v44, v44
	v_exp_f32_e32 v45, v45
	v_mfma_f32_32x32x16_bf16 v[2:17], v[212:215], v[50:53], v[2:17]
	s_mul_i32 s63, s61, 0x3000
	s_add_i32 s4, s62, 2
	s_cmp_ge_u32 s4, s90
	s_cbranch_scc1 .Lat_u2x_nodma
	s_add_i32 s4, s63, 0xffffd000
	s_cmp_lg_u32 s61, 0
	s_cselect_b32 s4, s4, 0x6000
	s_add_i32 s5, s4, s58
	s_mov_b32 m0, s5
	s_add_i32 s4, s4, s59
	global_load_lds_dwordx4 v[126:127], off
	s_mov_b32 m0, s4
	s_cmp_lt_u32 s56, 4
	s_cbranch_scc0 .Lat_u2x_nok2
	global_load_lds_dwordx4 v[122:123], off

; __device__ __forceinline__ void cmask(f32x16& p0, f32x16& p1, int jb, int qrel, int hi) {
;     const float NEG = -INFINITY; const int kb = 64 * jb + 4 * hi;
; #pragma unroll
;     for (int r = 0; r < 16; ++r) { const int kv = kb + (r & 3) + 8 * (r >> 2); if (kv > qrel) p0[r] = NEG; if (kv + 32 > qrel) p1[r] = NEG; }
; }
.Lat_u2x_nodma:
	v_lshl_add_u64 v[126:127], v[126:127], 0, s[34:35]
	v_lshl_add_u64 v[122:123], v[122:123], 0, s[20:21]
	v_lshl_add_u64 v[124:125], v[124:125], 0, s[34:35]
	v_add_f32_e32 v157, v157, v44
	v_add_f32_e32 v157, v157, v45
	v_cvt_pk_bf16_f32 v39, v44, v45
	v_exp_f32_e32 v46, v46
	v_exp_f32_e32 v47, v47
	v_mfma_f32_32x32x16_bf16 v[18:33], v[200:203], v[54:57], v[18:33]
	v_add_f32_e32 v156, v156, v46
	v_add_f32_e32 v156, v156, v47
	v_cvt_pk_bf16_f32 v40, v46, v47
	v_exp_f32_e32 v48, v48
	v_exp_f32_e32 v49, v49
	v_mfma_f32_32x32x16_bf16 v[2:17], v[230:233], v[54:57], v[2:17]
	v_add_f32_e32 v157, v157, v48
	v_add_f32_e32 v157, v157, v49
	v_cvt_pk_bf16_f32 v41, v48, v49
	s_nop 1
	v_mfma_f32_32x32x16_bf16 v[18:33], v[204:207], v[34:37], v[18:33]
	v_mfma_f32_32x32x16_bf16 v[2:17], v[234:237], v[34:37], v[2:17]
	v_mfma_f32_32x32x16_bf16 v[18:33], v[208:211], v[38:41], v[18:33]
	v_mfma_f32_32x32x16_bf16 v[2:17], v[164:167], v[38:41], v[2:17]
	v_add_f32_e32 v156, v156, v157
	v_add_f32_e32 v128, v128, v156
	s_cmp_lt_u32 s62, s91
	s_cbranch_scc1 .Lat_u2x_nomask
	s_sub_i32 s4, s62, s91
	s_lshl_b32 s4, s4, 6
	s_nop 7
	s_nop 7
	v_lshl_add_u32 v133, v142, 2, s4
	v_sub_u32_e32 v133, v145, v133
	s_nop 0
	v_cmp_gt_i32_e32 vcc, 0, v133
	v_cmp_gt_i32_e64 s[4:5], 1, v133
	v_cmp_gt_i32_e64 s[54:55], 2, v133
	v_cndmask_b32_e32 v238, v238, v220, vcc
	v_cmp_gt_i32_e32 vcc, 3, v133
	v_cndmask_b32_e64 v239, v239, v220, s[4:5]
	v_cmp_gt_i32_e64 s[4:5], 8, v133
	v_cndmask_b32_e64 v240, v240, v220, s[54:55]
	v_cmp_gt_i32_e64 s[54:55], 9, v133
	v_cndmask_b32_e32 v241, v241, v220, vcc
	v_cmp_gt_i32_e32 vcc, 10, v133
	v_cndmask_b32_e64 v242, v242, v220, s[4:5]
	v_cmp_gt_i32_e64 s[4:5], 11, v133
	v_cndmask_b32_e64 v243, v243, v220, s[54:55]
	v_cmp_gt_i32_e64 s[54:55], 16, v133
	v_cndmask_b32_e32 v244, v244, v220, vcc
	v_cmp_gt_i32_e32 vcc, 17, v133
	v_cndmask_b32_e64 v245, v245, v220, s[4:5]
	v_cmp_gt_i32_e64 s[4:5], 18, v133
	v_cndmask_b32_e64 v246, v246, v220, s[54:55]
	v_cmp_gt_i32_e64 s[54:55], 19, v133
	v_cndmask_b32_e32 v247, v247, v220, vcc
	v_cmp_gt_i32_e32 vcc, 24, v133
	v_cndmask_b32_e64 v248, v248, v220, s[4:5]
	v_cmp_gt_i32_e64 s[4:5], 25, v133
	v_cndmask_b32_e64 v249, v249, v220, s[54:55]
	v_cmp_gt_i32_e64 s[54:55], 26, v133
	v_cndmask_b32_e32 v250, v250, v220, vcc
	v_cmp_gt_i32_e32 vcc, 27, v133
	v_cndmask_b32_e64 v251, v251, v220, s[4:5]
	v_cmp_gt_i32_e64 s[4:5], 32, v133
	v_cndmask_b32_e64 v252, v252, v220, s[54:55]
	v_cmp_gt_i32_e64 s[54:55], 33, v133
	v_cndmask_b32_e32 v253, v253, v220, vcc
	v_cmp_gt_i32_e32 vcc, 34, v133
	v_cndmask_b32_e64 v180, v180, v220, s[4:5]
	v_cmp_gt_i32_e64 s[4:5], 35, v133
	v_cndmask_b32_e64 v181, v181, v220, s[54:55]
	v_cmp_gt_i32_e64 s[54:55], 40, v133
	v_cndmask_b32_e32 v182, v182, v220, vcc
	v_cmp_gt_i32_e32 vcc, 41, v133
	v_cndmask_b32_e64 v183, v183, v220, s[4:5]
	v_cmp_gt_i32_e64 s[4:5], 42, v133
	v_cndmask_b32_e64 v184, v184, v220, s[54:55]
	v_cmp_gt_i32_e64 s[54:55], 43, v133
	v_cndmask_b32_e32 v185, v185, v220, vcc
	v_cmp_gt_i32_e32 vcc, 48, v133
	v_cndmask_b32_e64 v186, v186, v220, s[4:5]
	v_cmp_gt_i32_e64 s[4:5], 49, v133
	v_cndmask_b32_e64 v187, v187, v220, s[54:55]
	v_cmp_gt_i32_e64 s[54:55], 50, v133
	v_cndmask_b32_e32 v188, v188, v220, vcc
	v_cmp_gt_i32_e32 vcc, 51, v133
	v_cndmask_b32_e64 v189, v189, v220, s[4:5]
	v_cmp_gt_i32_e64 s[4:5], 56, v133
	v_cndmask_b32_e64 v190, v190, v220, s[54:55]
	v_cmp_gt_i32_e64 s[54:55], 57, v133
	v_cndmask_b32_e32 v191, v191, v220, vcc
	v_cmp_gt_i32_e32 vcc, 58, v133
	v_cndmask_b32_e64 v192, v192, v220, s[4:5]
	v_cmp_gt_i32_e64 s[4:5], 59, v133
	v_cndmask_b32_e64 v193, v193, v220, s[54:55]
	v_cndmask_b32_e32 v194, v194, v220, vcc
	v_cndmask_b32_e64 v195, v195, v220, s[4:5]

; #define LAS __attribute__((address_space(3)))
; #define DMA_TILE(t, ks, vs) do { glds16(ksrc + (long)(t) * KVBLK * KNP, (unsigned)__builtin_amdgcn_readfirstlane(kdst + (ks) * KSLOT)); \
;         glds16(k2src + (long)(t) * KVBLK * KPP, (unsigned)__builtin_amdgcn_readfirstlane(k2dst + (ks) * KSLOT)); \
;         glds16(vsrc + (long)(t) * KVBLK * VP, (unsigned)__builtin_amdgcn_readfirstlane(vdst + (vs) * VSLOT)); } while (0)
; __device__ __forceinline__ void attn_unit(int b, int h, int qb, const bf16* Q, const bf16* __restrict__ Kn, const bf16* __restrict__ Kpe, const bf16* __restrict__ V, bf16* O, float* ASS, LAS char* shm) {
;     ...
;     const int vb0 = (int)(lds0 + LDS_V) + ((lane >> 4) & 1) * 32 + (lane & 3) * 8 + (4 * hi + ((lane & 15) >> 2)) * 64;
;     const int NT = (q0 + QB) / KVBLK;
;     DMA_TILE(0, 0, 0); DMA_TILE(1, 1, 1);
;     bf16x8 qr[6];
; #pragma unroll
;     for (int d0 = 0; d0 < 6; ++d0) qr[d0] = *reinterpret_cast<const bf16x8*>(&Qw[(long)r32 * QP + d0 * 16 + hi * 8]);
;     asm volatile("" : "+v"(qr[0]), "+v"(qr[1]), "+v"(qr[2]), "+v"(qr[3]), "+v"(qr[4]), "+v"(qr[5]));
;     float m_run = -1e30f, l_run = 0.f; f32x16 o[2]; o[0] = f32x16{}; o[1] = f32x16{};
;     const int qrel = wid * QBLK + r32;
;     f32x16 p0, p1;
;     bf16x8 kf[12]; s16x4 vlo[8], vhi[8]; u32x4 pw0, pw1, pw2, pw3;
;     const LAS char* kp0 = shm + LDS_K + hi * 1024 + r32 * 16;
;     const LAS char* vp0 = shm + LDS_V + ((lane >> 4) & 1) * 32 + (lane & 3) * 8 + (4 * hi + ((lane & 15) >> 2)) * 64;
.Lat_u2y_bar:
	s_barrier
	s_lshr_b32 s4, s56, 1
	s_sub_u32 s4, s62, s4
	s_cmp_gt_i32 s4, s91
	s_cbranch_scc1 .Lat_u2y_noqk
	s_mul_i32 s63, s61, 0x3000
	v_add_u32_e32 v158, s63, v146
	ds_read_b128 v[196:199], v158
	ds_read_b128 v[200:203], v158 offset:512
	ds_read_b128 v[204:207], v158 offset:2048
	ds_read_b128 v[208:211], v158 offset:2560
	ds_read_b128 v[212:215], v158 offset:4096
	ds_read_b128 v[230:233], v158 offset:4608
	ds_read_b128 v[234:237], v158 offset:6144
	ds_read_b128 v[164:167], v158 offset:6656
	ds_read_b128 v[168:171], v158 offset:8192
	ds_read_b128 v[172:175], v158 offset:8704
	ds_read_b128 v[148:151], v158 offset:10240
	ds_read_b128 v[152:155], v158 offset:10752
	s_lshl_b32 s4, s64, 13
	s_add_i32 s4, s4, 0x6000
	s_and_b32 s4, s4, 0x6000
	v_add_u32_e32 v159, s4, v143
	s_waitcnt lgkmcnt(11)
	v_mfma_f32_32x32x16_bf16 v[50:65], v[196:199], v[86:89], v[104:119]
	ds_read_b64_tr_b16 v[196:197], v159 offset:36864
	ds_read_b64_tr_b16 v[198:199], v159 offset:37376
	v_exp_f32_e32 v238, v238
	v_exp_f32_e32 v239, v239
	v_exp_f32_e32 v240, v240
	v_exp_f32_e32 v241, v241
	s_waitcnt lgkmcnt(12)
	v_mfma_f32_32x32x16_bf16 v[34:49], v[200:203], v[86:89], v[104:119]
	ds_read_b64_tr_b16 v[200:201], v159 offset:37888
	ds_read_b64_tr_b16 v[202:203], v159 offset:38400
	v_add_f32_e32 v156, v238, v239
	v_cvt_pk_bf16_f32 v238, v238, v239
	v_add_f32_e32 v157, v240, v241
	v_cvt_pk_bf16_f32 v239, v240, v241
	v_exp_f32_e32 v242, v242
	v_exp_f32_e32 v243, v243
	s_waitcnt lgkmcnt(13)
	v_mfma_f32_32x32x16_bf16 v[50:65], v[204:207], v[82:85], v[50:65]
	ds_read_b64_tr_b16 v[204:205], v159 offset:38912
	ds_read_b64_tr_b16 v[206:207], v159 offset:39424
	v_add_f32_e32 v156, v156, v242
	v_add_f32_e32 v156, v156, v243
	v_cvt_pk_bf16_f32 v240, v242, v243
	v_exp_f32_e32 v244, v244
	v_exp_f32_e32 v245, v245
	s_waitcnt lgkmcnt(14)
	v_mfma_f32_32x32x16_bf16 v[34:49], v[208:211], v[82:85], v[34:49]
	ds_read_b64_tr_b16 v[208:209], v159 offset:39936
	ds_read_b64_tr_b16 v[210:211], v159 offset:40448
	v_add_f32_e32 v157, v157, v244
	v_add_f32_e32 v157, v157, v245
	v_cvt_pk_bf16_f32 v241, v244, v245
	v_exp_f32_e32 v246, v246
	v_exp_f32_e32 v247, v247
	s_waitcnt lgkmcnt(15)
	v_mfma_f32_32x32x16_bf16 v[50:65], v[212:215], v[78:81], v[50:65]
	ds_read_b64_tr_b16 v[212:213], v159 offset:40960
	ds_read_b64_tr_b16 v[214:215], v159 offset:41472
	v_add_f32_e32 v156, v156, v246
	v_add_f32_e32 v156, v156, v247
	v_cvt_pk_bf16_f32 v242, v246, v247
	v_exp_f32_e32 v248, v248
	v_exp_f32_e32 v249, v249
	s_waitcnt lgkmcnt(15)
	v_mfma_f32_32x32x16_bf16 v[34:49], v[230:233], v[78:81], v[34:49]
	ds_read_b64_tr_b16 v[230:231], v159 offset:41984
	ds_read_b64_tr_b16 v[232:233], v159 offset:42496
	v_add_f32_e32 v157, v157, v248
	v_add_f32_e32 v157, v157, v249
	v_cvt_pk_bf16_f32 v243, v248, v249
	v_exp_f32_e32 v250, v250
	v_exp_f32_e32 v251, v251
	s_waitcnt lgkmcnt(15)
	v_mfma_f32_32x32x16_bf16 v[50:65], v[234:237], v[74:77], v[50:65]
	ds_read_b64_tr_b16 v[234:235], v159 offset:43008
	ds_read_b64_tr_b16 v[236:237], v159 offset:43520
	v_add_f32_e32 v156, v156, v250
	v_add_f32_e32 v156, v156, v251
	v_cvt_pk_bf16_f32 v244, v250, v251
	v_exp_f32_e32 v252, v252
	v_exp_f32_e32 v253, v253
	s_waitcnt lgkmcnt(15)
	v_mfma_f32_32x32x16_bf16 v[34:49], v[164:167], v[74:77], v[34:49]
	ds_read_b64_tr_b16 v[164:165], v159 offset:44032
	ds_read_b64_tr_b16 v[166:167], v159 offset:44544
	v_add_f32_e32 v157, v157, v252
	v_add_f32_e32 v157, v157, v253
	v_cvt_pk_bf16_f32 v245, v252, v253
	v_exp_f32_e32 v180, v180
	v_exp_f32_e32 v181, v181
	s_waitcnt lgkmcnt(15)
	v_mfma_f32_32x32x16_bf16 v[50:65], v[168:171], v[70:73], v[50:65]
	v_add_f32_e32 v156, v156, v180
	v_add_f32_e32 v156, v156, v181
	v_cvt_pk_bf16_f32 v180, v180, v181
	v_exp_f32_e32 v182, v182
	v_exp_f32_e32 v183, v183
	s_waitcnt lgkmcnt(15)
	v_mfma_f32_32x32x16_bf16 v[34:49], v[172:175], v[70:73], v[34:49]
	v_add_f32_e32 v157, v157, v182
	v_add_f32_e32 v157, v157, v183
	v_cvt_pk_bf16_f32 v181, v182, v183
	v_exp_f32_e32 v184, v184
	v_exp_f32_e32 v185, v185
	s_waitcnt lgkmcnt(15)
	v_mfma_f32_32x32x16_bf16 v[50:65], v[148:151], v[66:69], v[50:65]
	v_add_f32_e32 v156, v156, v184
	v_add_f32_e32 v156, v156, v185
	v_cvt_pk_bf16_f32 v182, v184, v185
	v_exp_f32_e32 v186, v186
	v_exp_f32_e32 v187, v187
	s_waitcnt lgkmcnt(15)
	v_mfma_f32_32x32x16_bf16 v[34:49], v[152:155], v[66:69], v[34:49]
	v_add_f32_e32 v157, v157, v186
	v_add_f32_e32 v157, v157, v187
	v_cvt_pk_bf16_f32 v183, v186, v187
	v_exp_f32_e32 v188, v188
	v_exp_f32_e32 v189, v189
	s_waitcnt lgkmcnt(0)
	v_mfma_f32_32x32x16_bf16 v[18:33], v[196:199], v[238:241], v[18:33]
	v_add_f32_e32 v156, v156, v188
	v_add_f32_e32 v156, v156, v189
	v_cvt_pk_bf16_f32 v184, v188, v189
	v_exp_f32_e32 v190, v190
	v_exp_f32_e32 v191, v191
	v_mfma_f32_32x32x16_bf16 v[2:17], v[212:215], v[238:241], v[2:17]
	s_mul_i32 s63, s61, 0x3000
	s_add_i32 s4, s62, 2
	s_cmp_ge_u32 s4, s90
	s_cbranch_scc1 .Lat_u2y_nodma
	s_add_i32 s4, s63, 0xffffd000
	s_cmp_lg_u32 s61, 0
	s_cselect_b32 s4, s4, 0x6000
	s_add_i32 s5, s4, s58
	s_mov_b32 m0, s5
	s_add_i32 s4, s4, s59
	global_load_lds_dwordx4 v[126:127], off
	s_mov_b32 m0, s4
	s_cmp_lt_u32 s56, 4
	s_cbranch_scc0 .Lat_u2y_nok2
	global_load_lds_dwordx4 v[122:123], off

; __device__ __forceinline__ void cmask(f32x16& p0, f32x16& p1, int jb, int qrel, int hi) {
;     const float NEG = -INFINITY; const int kb = 64 * jb + 4 * hi;
; #pragma unroll
;     for (int r = 0; r < 16; ++r) { const int kv = kb + (r & 3) + 8 * (r >> 2); if (kv > qrel) p0[r] = NEG; if (kv + 32 > qrel) p1[r] = NEG; }
; }
.Lat_u2y_nodma:
	v_lshl_add_u64 v[126:127], v[126:127], 0, s[34:35]
	v_lshl_add_u64 v[122:123], v[122:123], 0, s[20:21]
	v_lshl_add_u64 v[124:125], v[124:125], 0, s[34:35]
	v_add_f32_e32 v157, v157, v190
	v_add_f32_e32 v157, v157, v191
	v_cvt_pk_bf16_f32 v185, v190, v191
	v_exp_f32_e32 v192, v192
	v_exp_f32_e32 v193, v193
	v_mfma_f32_32x32x16_bf16 v[18:33], v[200:203], v[242:245], v[18:33]
	v_add_f32_e32 v156, v156, v192
	v_add_f32_e32 v156, v156, v193
	v_cvt_pk_bf16_f32 v186, v192, v193
	v_exp_f32_e32 v194, v194
	v_exp_f32_e32 v195, v195
	v_mfma_f32_32x32x16_bf16 v[2:17], v[230:233], v[242:245], v[2:17]
	v_add_f32_e32 v157, v157, v194
	v_add_f32_e32 v157, v157, v195
	v_cvt_pk_bf16_f32 v187, v194, v195
	s_nop 1
	v_mfma_f32_32x32x16_bf16 v[18:33], v[204:207], v[180:183], v[18:33]
	v_mfma_f32_32x32x16_bf16 v[2:17], v[234:237], v[180:183], v[2:17]
	v_mfma_f32_32x32x16_bf16 v[18:33], v[208:211], v[184:187], v[18:33]
	v_mfma_f32_32x32x16_bf16 v[2:17], v[164:167], v[184:187], v[2:17]
	v_add_f32_e32 v156, v156, v157
	v_add_f32_e32 v128, v128, v156
	s_cmp_lt_u32 s62, s91
	s_cbranch_scc1 .Lat_u2y_nomask
	s_sub_i32 s4, s62, s91
	s_lshl_b32 s4, s4, 6
	s_nop 7
	s_nop 7
	v_lshl_add_u32 v133, v142, 2, s4
	v_sub_u32_e32 v133, v145, v133
	s_nop 0
	v_cmp_gt_i32_e32 vcc, 0, v133
	v_cmp_gt_i32_e64 s[4:5], 1, v133
	v_cmp_gt_i32_e64 s[54:55], 2, v133
	v_cndmask_b32_e32 v50, v50, v220, vcc
	v_cmp_gt_i32_e32 vcc, 3, v133
	v_cndmask_b32_e64 v51, v51, v220, s[4:5]
	v_cmp_gt_i32_e64 s[4:5], 8, v133
	v_cndmask_b32_e64 v52, v52, v220, s[54:55]
	v_cmp_gt_i32_e64 s[54:55], 9, v133
	v_cndmask_b32_e32 v53, v53, v220, vcc
	v_cmp_gt_i32_e32 vcc, 10, v133
	v_cndmask_b32_e64 v54, v54, v220, s[4:5]
	v_cmp_gt_i32_e64 s[4:5], 11, v133
	v_cndmask_b32_e64 v55, v55, v220, s[54:55]
	v_cmp_gt_i32_e64 s[54:55], 16, v133
	v_cndmask_b32_e32 v56, v56, v220, vcc
	v_cmp_gt_i32_e32 vcc, 17, v133
	v_cndmask_b32_e64 v57, v57, v220, s[4:5]
	v_cmp_gt_i32_e64 s[4:5], 18, v133
	v_cndmask_b32_e64 v58, v58, v220, s[54:55]
	v_cmp_gt_i32_e64 s[54:55], 19, v133
	v_cndmask_b32_e32 v59, v59, v220, vcc
	v_cmp_gt_i32_e32 vcc, 24, v133
	v_cndmask_b32_e64 v60, v60, v220, s[4:5]
	v_cmp_gt_i32_e64 s[4:5], 25, v133
	v_cndmask_b32_e64 v61, v61, v220, s[54:55]
	v_cmp_gt_i32_e64 s[54:55], 26, v133
	v_cndmask_b32_e32 v62, v62, v220, vcc
	v_cmp_gt_i32_e32 vcc, 27, v133
	v_cndmask_b32_e64 v63, v63, v220, s[4:5]
	v_cmp_gt_i32_e64 s[4:5], 32, v133
	v_cndmask_b32_e64 v64, v64, v220, s[54:55]
	v_cmp_gt_i32_e64 s[54:55], 33, v133
	v_cndmask_b32_e32 v65, v65, v220, vcc
	v_cmp_gt_i32_e32 vcc, 34, v133
	v_cndmask_b32_e64 v34, v34, v220, s[4:5]
	v_cmp_gt_i32_e64 s[4:5], 35, v133
	v_cndmask_b32_e64 v35, v35, v220, s[54:55]
	v_cmp_gt_i32_e64 s[54:55], 40, v133
	v_cndmask_b32_e32 v36, v36, v220, vcc
	v_cmp_gt_i32_e32 vcc, 41, v133
	v_cndmask_b32_e64 v37, v37, v220, s[4:5]
	v_cmp_gt_i32_e64 s[4:5], 42, v133
	v_cndmask_b32_e64 v38, v38, v220, s[54:55]
	v_cmp_gt_i32_e64 s[54:55], 43, v133
	v_cndmask_b32_e32 v39, v39, v220, vcc
	v_cmp_gt_i32_e32 vcc, 48, v133
	v_cndmask_b32_e64 v40, v40, v220, s[4:5]
	v_cmp_gt_i32_e64 s[4:5], 49, v133
	v_cndmask_b32_e64 v41, v41, v220, s[54:55]
	v_cmp_gt_i32_e64 s[54:55], 50, v133
	v_cndmask_b32_e32 v42, v42, v220, vcc
	v_cmp_gt_i32_e32 vcc, 51, v133
	v_cndmask_b32_e64 v43, v43, v220, s[4:5]
	v_cmp_gt_i32_e64 s[4:5], 56, v133
	v_cndmask_b32_e64 v44, v44, v220, s[54:55]
	v_cmp_gt_i32_e64 s[54:55], 57, v133
	v_cndmask_b32_e32 v45, v45, v220, vcc
	v_cmp_gt_i32_e32 vcc, 58, v133
	v_cndmask_b32_e64 v46, v46, v220, s[4:5]
	v_cmp_gt_i32_e64 s[4:5], 59, v133
	v_cndmask_b32_e64 v47, v47, v220, s[54:55]
	v_cndmask_b32_e32 v48, v48, v220, vcc
	v_cndmask_b32_e64 v49, v49, v220, s[4:5]

.Lat_u2_nowarm:
	s_waitcnt lgkmcnt(0)
	s_lshr_b32 s4, s56, 1
	s_sub_u32 s4, s62, s4
	s_sub_u32 s4, s4, 1
	s_cmp_gt_i32 s4, s91
	s_cbranch_scc1 .Lat_u2t_skip
	s_lshl_b32 s4, s64, 13
	s_add_i32 s4, s4, 0x6000
	s_and_b32 s4, s4, 0x6000
	v_add_u32_e32 v159, s4, v143
	ds_read_b64_tr_b16 v[196:197], v159 offset:36864
	ds_read_b64_tr_b16 v[198:199], v159 offset:37376
	ds_read_b64_tr_b16 v[200:201], v159 offset:37888
	ds_read_b64_tr_b16 v[202:203], v159 offset:38400
	ds_read_b64_tr_b16 v[204:205], v159 offset:38912
	ds_read_b64_tr_b16 v[206:207], v159 offset:39424
	ds_read_b64_tr_b16 v[208:209], v159 offset:39936
	ds_read_b64_tr_b16 v[210:211], v159 offset:40448
	ds_read_b64_tr_b16 v[212:213], v159 offset:40960
	ds_read_b64_tr_b16 v[214:215], v159 offset:41472
	ds_read_b64_tr_b16 v[230:231], v159 offset:41984
	ds_read_b64_tr_b16 v[232:233], v159 offset:42496
	ds_read_b64_tr_b16 v[234:235], v159 offset:43008
	ds_read_b64_tr_b16 v[236:237], v159 offset:43520
	ds_read_b64_tr_b16 v[164:165], v159 offset:44032
	ds_read_b64_tr_b16 v[166:167], v159 offset:44544
	v_exp_f32_e32 v238, v238
	v_exp_f32_e32 v239, v239
	v_exp_f32_e32 v240, v240
	v_exp_f32_e32 v241, v241
	v_add_f32_e32 v156, v238, v239
	v_cvt_pk_bf16_f32 v238, v238, v239
	v_add_f32_e32 v157, v240, v241
	v_cvt_pk_bf16_f32 v239, v240, v241
	v_exp_f32_e32 v242, v242
	v_exp_f32_e32 v243, v243
	v_add_f32_e32 v156, v156, v242
	v_add_f32_e32 v156, v156, v243
	v_cvt_pk_bf16_f32 v240, v242, v243
	v_exp_f32_e32 v244, v244
	v_exp_f32_e32 v245, v245
	v_add_f32_e32 v157, v157, v244
	v_add_f32_e32 v157, v157, v245
	v_cvt_pk_bf16_f32 v241, v244, v245
	v_exp_f32_e32 v246, v246
	v_exp_f32_e32 v247, v247
	v_add_f32_e32 v156, v156, v246
	v_add_f32_e32 v156, v156, v247
	v_cvt_pk_bf16_f32 v242, v246, v247
	v_exp_f32_e32 v248, v248
	v_exp_f32_e32 v249, v249
	v_add_f32_e32 v157, v157, v248
	v_add_f32_e32 v157, v157, v249
	v_cvt_pk_bf16_f32 v243, v248, v249
	v_exp_f32_e32 v250, v250
	v_exp_f32_e32 v251, v251
	v_add_f32_e32 v156, v156, v250
	v_add_f32_e32 v156, v156, v251
	v_cvt_pk_bf16_f32 v244, v250, v251
	v_exp_f32_e32 v252, v252
	v_exp_f32_e32 v253, v253
	v_add_f32_e32 v157, v157, v252
	v_add_f32_e32 v157, v157, v253
	v_cvt_pk_bf16_f32 v245, v252, v253
	v_exp_f32_e32 v180, v180
	v_exp_f32_e32 v181, v181
	v_add_f32_e32 v156, v156, v180
	v_add_f32_e32 v156, v156, v181
	v_cvt_pk_bf16_f32 v180, v180, v181
	v_exp_f32_e32 v182, v182
	v_exp_f32_e32 v183, v183
	v_add_f32_e32 v157, v157, v182
	v_add_f32_e32 v157, v157, v183
	v_cvt_pk_bf16_f32 v181, v182, v183
	v_exp_f32_e32 v184, v184
	v_exp_f32_e32 v185, v185
	v_add_f32_e32 v156, v156, v184
	v_add_f32_e32 v156, v156, v185
	v_cvt_pk_bf16_f32 v182, v184, v185
	v_exp_f32_e32 v186, v186
	v_exp_f32_e32 v187, v187
	v_add_f32_e32 v157, v157, v186
	v_add_f32_e32 v157, v157, v187
	v_cvt_pk_bf16_f32 v183, v186, v187
	v_exp_f32_e32 v188, v188
	v_exp_f32_e32 v189, v189
	v_add_f32_e32 v156, v156, v188
	v_add_f32_e32 v156, v156, v189
	v_cvt_pk_bf16_f32 v184, v188, v189
	v_exp_f32_e32 v190, v190
	v_exp_f32_e32 v191, v191
	v_add_f32_e32 v157, v157, v190
	v_add_f32_e32 v157, v157, v191
	v_cvt_pk_bf16_f32 v185, v190, v191
	v_exp_f32_e32 v192, v192
	v_exp_f32_e32 v193, v193
	v_add_f32_e32 v156, v156, v192
	v_add_f32_e32 v156, v156, v193
	v_cvt_pk_bf16_f32 v186, v192, v193
	v_exp_f32_e32 v194, v194
	v_exp_f32_e32 v195, v195
	v_add_f32_e32 v157, v157, v194
	v_add_f32_e32 v157, v157, v195
	v_cvt_pk_bf16_f32 v187, v194, v195
	v_add_f32_e32 v156, v156, v157
	v_add_f32_e32 v128, v128, v156
	s_waitcnt lgkmcnt(0)
	v_mfma_f32_32x32x16_bf16 v[18:33], v[196:199], v[238:241], v[18:33]
	v_mfma_f32_32x32x16_bf16 v[2:17], v[212:215], v[238:241], v[2:17]
	v_mfma_f32_32x32x16_bf16 v[18:33], v[200:203], v[242:245], v[18:33]
	v_mfma_f32_32x32x16_bf16 v[2:17], v[230:233], v[242:245], v[2:17]
	v_mfma_f32_32x32x16_bf16 v[18:33], v[204:207], v[180:183], v[18:33]
	v_mfma_f32_32x32x16_bf16 v[2:17], v[234:237], v[180:183], v[2:17]
	v_mfma_f32_32x32x16_bf16 v[18:33], v[208:211], v[184:187], v[18:33]
	v_mfma_f32_32x32x16_bf16 v[2:17], v[164:167], v[184:187], v[2:17]

.Lat_u2x_noqk:
	s_lshr_b32 s4, s56, 1
	s_sub_u32 s4, s62, s4
	s_sub_u32 s4, s4, 1
	s_cmp_gt_i32 s4, s91
	s_cbranch_scc1 .Lat_u2x_idle
	s_lshl_b32 s4, s64, 13
	s_add_i32 s4, s4, 0x6000
	s_and_b32 s4, s4, 0x6000
	v_add_u32_e32 v159, s4, v143
	ds_read_b64_tr_b16 v[196:197], v159 offset:36864
	ds_read_b64_tr_b16 v[198:199], v159 offset:37376
	ds_read_b64_tr_b16 v[200:201], v159 offset:37888
	ds_read_b64_tr_b16 v[202:203], v159 offset:38400
	ds_read_b64_tr_b16 v[204:205], v159 offset:38912
	ds_read_b64_tr_b16 v[206:207], v159 offset:39424
	ds_read_b64_tr_b16 v[208:209], v159 offset:39936
	ds_read_b64_tr_b16 v[210:211], v159 offset:40448
	ds_read_b64_tr_b16 v[212:213], v159 offset:40960
	ds_read_b64_tr_b16 v[214:215], v159 offset:41472
	ds_read_b64_tr_b16 v[230:231], v159 offset:41984
	ds_read_b64_tr_b16 v[232:233], v159 offset:42496
	ds_read_b64_tr_b16 v[234:235], v159 offset:43008
	ds_read_b64_tr_b16 v[236:237], v159 offset:43520
	ds_read_b64_tr_b16 v[164:165], v159 offset:44032
	ds_read_b64_tr_b16 v[166:167], v159 offset:44544
	v_exp_f32_e32 v50, v50
	v_exp_f32_e32 v51, v51
	v_exp_f32_e32 v52, v52
	v_exp_f32_e32 v53, v53
	v_add_f32_e32 v156, v50, v51
	v_cvt_pk_bf16_f32 v50, v50, v51
	v_add_f32_e32 v157, v52, v53
	v_cvt_pk_bf16_f32 v51, v52, v53
	v_exp_f32_e32 v54, v54
	v_exp_f32_e32 v55, v55
	v_add_f32_e32 v156, v156, v54
	v_add_f32_e32 v156, v156, v55
	v_cvt_pk_bf16_f32 v52, v54, v55
	v_exp_f32_e32 v56, v56
	v_exp_f32_e32 v57, v57
	v_add_f32_e32 v157, v157, v56
	v_add_f32_e32 v157, v157, v57
	v_cvt_pk_bf16_f32 v53, v56, v57
	v_exp_f32_e32 v58, v58
	v_exp_f32_e32 v59, v59
	v_add_f32_e32 v156, v156, v58
	v_add_f32_e32 v156, v156, v59
	v_cvt_pk_bf16_f32 v54, v58, v59
	v_exp_f32_e32 v60, v60
	v_exp_f32_e32 v61, v61
	v_add_f32_e32 v157, v157, v60
	v_add_f32_e32 v157, v157, v61
	v_cvt_pk_bf16_f32 v55, v60, v61
	v_exp_f32_e32 v62, v62
	v_exp_f32_e32 v63, v63
	v_add_f32_e32 v156, v156, v62
	v_add_f32_e32 v156, v156, v63
	v_cvt_pk_bf16_f32 v56, v62, v63
	v_exp_f32_e32 v64, v64
	v_exp_f32_e32 v65, v65
	v_add_f32_e32 v157, v157, v64
	v_add_f32_e32 v157, v157, v65
	v_cvt_pk_bf16_f32 v57, v64, v65
	v_exp_f32_e32 v34, v34
	s_nop 1
	s_waitcnt lgkmcnt(0)
	v_mfma_f32_32x32x16_bf16 v[18:33], v[196:199], v[50:53], v[18:33]
	v_exp_f32_e32 v35, v35
	v_add_f32_e32 v156, v156, v34
	v_add_f32_e32 v156, v156, v35
	v_cvt_pk_bf16_f32 v34, v34, v35
	v_exp_f32_e32 v36, v36
	v_exp_f32_e32 v37, v37
	v_add_f32_e32 v157, v157, v36
	v_add_f32_e32 v157, v157, v37
	v_cvt_pk_bf16_f32 v35, v36, v37
	v_exp_f32_e32 v38, v38
	v_mfma_f32_32x32x16_bf16 v[2:17], v[212:215], v[50:53], v[2:17]
	v_exp_f32_e32 v39, v39
	v_add_f32_e32 v156, v156, v38
	v_add_f32_e32 v156, v156, v39
	v_cvt_pk_bf16_f32 v36, v38, v39
	v_exp_f32_e32 v40, v40
	v_exp_f32_e32 v41, v41
	v_add_f32_e32 v157, v157, v40
	v_add_f32_e32 v157, v157, v41
	v_cvt_pk_bf16_f32 v37, v40, v41
	v_exp_f32_e32 v42, v42
	v_mfma_f32_32x32x16_bf16 v[18:33], v[200:203], v[54:57], v[18:33]
	v_exp_f32_e32 v43, v43
	v_add_f32_e32 v156, v156, v42
	v_add_f32_e32 v156, v156, v43
	v_cvt_pk_bf16_f32 v38, v42, v43
	v_exp_f32_e32 v44, v44
	v_exp_f32_e32 v45, v45
	v_add_f32_e32 v157, v157, v44
	v_add_f32_e32 v157, v157, v45
	v_cvt_pk_bf16_f32 v39, v44, v45
	v_exp_f32_e32 v46, v46
	v_mfma_f32_32x32x16_bf16 v[2:17], v[230:233], v[54:57], v[2:17]
	v_exp_f32_e32 v47, v47
	v_add_f32_e32 v156, v156, v46
	v_add_f32_e32 v156, v156, v47
	v_cvt_pk_bf16_f32 v40, v46, v47
	v_exp_f32_e32 v48, v48
	v_exp_f32_e32 v49, v49
	v_add_f32_e32 v157, v157, v48
	v_add_f32_e32 v157, v157, v49
	v_cvt_pk_bf16_f32 v41, v48, v49
	s_nop 1
	v_mfma_f32_32x32x16_bf16 v[18:33], v[204:207], v[34:37], v[18:33]
	v_mfma_f32_32x32x16_bf16 v[2:17], v[234:237], v[34:37], v[2:17]
	v_mfma_f32_32x32x16_bf16 v[18:33], v[208:211], v[38:41], v[18:33]
	v_mfma_f32_32x32x16_bf16 v[2:17], v[164:167], v[38:41], v[2:17]
	v_add_f32_e32 v156, v156, v157
	v_add_f32_e32 v128, v128, v156

.Lat_u2y_noqk:
	s_lshr_b32 s4, s56, 1
	s_sub_u32 s4, s62, s4
	s_sub_u32 s4, s4, 1
	s_cmp_gt_i32 s4, s91
	s_cbranch_scc1 .Lat_u2y_idle
	s_lshl_b32 s4, s64, 13
	s_add_i32 s4, s4, 0x6000
	s_and_b32 s4, s4, 0x6000
	v_add_u32_e32 v159, s4, v143
	ds_read_b64_tr_b16 v[196:197], v159 offset:36864
	ds_read_b64_tr_b16 v[198:199], v159 offset:37376
	ds_read_b64_tr_b16 v[200:201], v159 offset:37888
	ds_read_b64_tr_b16 v[202:203], v159 offset:38400
	ds_read_b64_tr_b16 v[204:205], v159 offset:38912
	ds_read_b64_tr_b16 v[206:207], v159 offset:39424
	ds_read_b64_tr_b16 v[208:209], v159 offset:39936
	ds_read_b64_tr_b16 v[210:211], v159 offset:40448
	ds_read_b64_tr_b16 v[212:213], v159 offset:40960
	ds_read_b64_tr_b16 v[214:215], v159 offset:41472
	ds_read_b64_tr_b16 v[230:231], v159 offset:41984
	ds_read_b64_tr_b16 v[232:233], v159 offset:42496
	ds_read_b64_tr_b16 v[234:235], v159 offset:43008
	ds_read_b64_tr_b16 v[236:237], v159 offset:43520
	ds_read_b64_tr_b16 v[164:165], v159 offset:44032
	ds_read_b64_tr_b16 v[166:167], v159 offset:44544
	v_exp_f32_e32 v238, v238
	v_exp_f32_e32 v239, v239
	v_exp_f32_e32 v240, v240
	v_exp_f32_e32 v241, v241
	v_add_f32_e32 v156, v238, v239
	v_cvt_pk_bf16_f32 v238, v238, v239
	v_add_f32_e32 v157, v240, v241
	v_cvt_pk_bf16_f32 v239, v240, v241
	v_exp_f32_e32 v242, v242
	v_exp_f32_e32 v243, v243
	v_add_f32_e32 v156, v156, v242
	v_add_f32_e32 v156, v156, v243
	v_cvt_pk_bf16_f32 v240, v242, v243
	v_exp_f32_e32 v244, v244
	v_exp_f32_e32 v245, v245
	v_add_f32_e32 v157, v157, v244
	v_add_f32_e32 v157, v157, v245
	v_cvt_pk_bf16_f32 v241, v244, v245
	v_exp_f32_e32 v246, v246
	v_exp_f32_e32 v247, v247
	v_add_f32_e32 v156, v156, v246
	v_add_f32_e32 v156, v156, v247
	v_cvt_pk_bf16_f32 v242, v246, v247
	v_exp_f32_e32 v248, v248
	v_exp_f32_e32 v249, v249
	v_add_f32_e32 v157, v157, v248
	v_add_f32_e32 v157, v157, v249
	v_cvt_pk_bf16_f32 v243, v248, v249
	v_exp_f32_e32 v250, v250
	v_exp_f32_e32 v251, v251
	v_add_f32_e32 v156, v156, v250
	v_add_f32_e32 v156, v156, v251
	v_cvt_pk_bf16_f32 v244, v250, v251
	v_exp_f32_e32 v252, v252
	v_exp_f32_e32 v253, v253
	v_add_f32_e32 v157, v157, v252
	v_add_f32_e32 v157, v157, v253
	v_cvt_pk_bf16_f32 v245, v252, v253
	v_exp_f32_e32 v180, v180
	s_nop 1
	s_waitcnt lgkmcnt(0)
	v_mfma_f32_32x32x16_bf16 v[18:33], v[196:199], v[238:241], v[18:33]
	v_exp_f32_e32 v181, v181
	v_add_f32_e32 v156, v156, v180
	v_add_f32_e32 v156, v156, v181
	v_cvt_pk_bf16_f32 v180, v180, v181
	v_exp_f32_e32 v182, v182
	v_exp_f32_e32 v183, v183
	v_add_f32_e32 v157, v157, v182
	v_add_f32_e32 v157, v157, v183
	v_cvt_pk_bf16_f32 v181, v182, v183
	v_exp_f32_e32 v184, v184
	v_mfma_f32_32x32x16_bf16 v[2:17], v[212:215], v[238:241], v[2:17]
	v_exp_f32_e32 v185, v185
	v_add_f32_e32 v156, v156, v184
	v_add_f32_e32 v156, v156, v185
	v_cvt_pk_bf16_f32 v182, v184, v185
	v_exp_f32_e32 v186, v186
	v_exp_f32_e32 v187, v187
	v_add_f32_e32 v157, v157, v186
	v_add_f32_e32 v157, v157, v187
	v_cvt_pk_bf16_f32 v183, v186, v187
	v_exp_f32_e32 v188, v188
	v_mfma_f32_32x32x16_bf16 v[18:33], v[200:203], v[242:245], v[18:33]
	v_exp_f32_e32 v189, v189
	v_add_f32_e32 v156, v156, v188
	v_add_f32_e32 v156, v156, v189
	v_cvt_pk_bf16_f32 v184, v188, v189
	v_exp_f32_e32 v190, v190
	v_exp_f32_e32 v191, v191
	v_add_f32_e32 v157, v157, v190
	v_add_f32_e32 v157, v157, v191
	v_cvt_pk_bf16_f32 v185, v190, v191
	v_exp_f32_e32 v192, v192
	v_mfma_f32_32x32x16_bf16 v[2:17], v[230:233], v[242:245], v[2:17]
	v_exp_f32_e32 v193, v193
	v_add_f32_e32 v156, v156, v192
	v_add_f32_e32 v156, v156, v193
	v_cvt_pk_bf16_f32 v186, v192, v193
	v_exp_f32_e32 v194, v194
	v_exp_f32_e32 v195, v195
	v_add_f32_e32 v157, v157, v194
	v_add_f32_e32 v157, v157, v195
	v_cvt_pk_bf16_f32 v187, v194, v195
	s_nop 1
	v_mfma_f32_32x32x16_bf16 v[18:33], v[204:207], v[180:183], v[18:33]
	v_mfma_f32_32x32x16_bf16 v[2:17], v[234:237], v[180:183], v[2:17]
	v_mfma_f32_32x32x16_bf16 v[18:33], v[208:211], v[184:187], v[18:33]
	v_mfma_f32_32x32x16_bf16 v[2:17], v[164:167], v[184:187], v[2:17]
	v_add_f32_e32 v156, v156, v157
	v_add_f32_e32 v128, v128, v156
